# adds: saddr-form LDS-DMA staging loads (no VALU in the load segments) in the other six K-loops
# speedup vs baseline: 1.0048x; 1.0048x over previous
; #define PG8_STAGE(bufoff, gbase, voff) do { _Pragma("unroll") for (int _i = 0; _i < 2; ++_i) \
;         __builtin_amdgcn_global_load_lds((const unsigned*)((const char*)(gbase) + (voff)[_i]), (PG8_LAS unsigned*)(lds + (bufoff) + ldsw + _i * 8192), 16, 0, 0); } while (0)
; #define PG8_LDA(dst, b, h) do { _Pragma("unroll") for (int m = 0; m < 4; ++m) _Pragma("unroll") for (int k = 0; k < 2; ++k) dst[m][k] = *(const PG8_LAS bf16x8*)(lds + PG8_SA(b, h) + aoff + m * 2048 + k * 1024); } while (0)
; #define PG8_LDB(dst, b, h) do { _Pragma("unroll") for (int n = 0; n < 2; ++n) _Pragma("unroll") for (int k = 0; k < 2; ++k) dst[n][k] = *(const PG8_LAS bf16x8*)(lds + PG8_SB(b, h) + boff + n * 2048 + k * 1024); } while (0)
; #define PG8_MMA(ai, bj, At, Bt) do { __builtin_amdgcn_s_setprio(1); _Pragma("unroll") for (int m = 0; m < 4; ++m) _Pragma("unroll") for (int n = 0; n < 2; ++n) _Pragma("unroll") for (int k = 0; k < 2; ++k) \
;         acc[ai][bj][m][n] = __builtin_amdgcn_mfma_f32_16x16x32_bf16(Bt[n][k], At[m][k], acc[ai][bj][m][n], 0, 0, 0); __builtin_amdgcn_s_setprio(0); } while (0)
; #define PG8_WAIT_V(n) asm volatile("s_waitcnt vmcnt(" #n ")" ::: "memory")
; #define PG8_WAIT_L(n) asm volatile("s_waitcnt lgkmcnt(" #n ")" ::: "memory")
; #define PG8_BAR __builtin_amdgcn_s_barrier()
; #define PG8_SCHED __builtin_amdgcn_sched_barrier(0)
; template <class Epi, class Sched, bool ALIGN_EPI = false, bool SP2 = false, bool ACHUNK = false>
; __device__ __forceinline__ void gemm_phase(PG8_LAS unsigned char* lds, const Gemm g, const Sched& S, const Epi& E) {
;     ...
;             PG8_LDB(B0, 0, 0); PG8_LDB(B1, 0, 1); PG8_SCHED; PG8_LDA(At, 0, 0); PG8_STAGE(PG8_SA(1, 1), a1 + hstepA, voffA);
;             PG8_WAIT_V(8); PG8_WAIT_L(0); PG8_BAR; PG8_MMA(0, 0, At, B0); PG8_MMA(0, 1, At, B1); PG8_BAR; PG8_SCHED;
;             PG8_LDA(At, 0, 1); PG8_STAGE(PG8_SB(0, 0), b2, voffB); PG8_STAGE(PG8_SB(0, 1), b2 + hstepB, voffB); PG8_STAGE(PG8_SA(0, 0), a2, voffA);
;             PG8_WAIT_V(8); PG8_WAIT_L(0); PG8_BAR; PG8_MMA(1, 0, At, B0); PG8_MMA(1, 1, At, B1); PG8_BAR; PG8_SCHED;
.Lnl_dn:
	s_add_i32 s47, 0, 0x14000
	ds_read_b128 v[142:145], v151
	ds_read_b128 v[152:155], v151 offset:1024
	ds_read_b128 v[156:159], v151 offset:2048
	ds_read_b128 v[160:163], v151 offset:3072
	v_add_u32_e32 v151, s47, v147
	ds_read_b128 v[164:167], v151
	ds_read_b128 v[168:171], v151 offset:1024
	ds_read_b128 v[172:175], v151 offset:2048
	ds_read_b128 v[176:179], v151 offset:3072
	s_add_i32 m0, s23, 0xc000
	ds_read_b128 v[180:183], v150
	ds_read_b128 v[184:187], v150 offset:1024
	ds_read_b128 v[188:191], v150 offset:2048
	ds_read_b128 v[198:201], v150 offset:3072
	ds_read_b128 v[202:205], v150 offset:4096
	ds_read_b128 v[206:209], v150 offset:5120
	ds_read_b128 v[210:213], v150 offset:6144
	ds_read_b128 v[214:217], v150 offset:7168
	global_load_lds_dwordx4 v138, s[20:21]
	s_add_i32 m0, s23, 0xe000
	s_nop 0
	global_load_lds_dwordx4 v140, s[20:21]
	s_waitcnt vmcnt(8)
	s_waitcnt lgkmcnt(0)
	s_barrier
	s_setprio 1
	v_mfma_f32_16x16x32_bf16 v[120:123], v[142:145], v[180:183], v[120:123]
	v_mfma_f32_16x16x32_bf16 v[128:131], v[156:159], v[180:183], v[128:131]
	v_mfma_f32_16x16x32_bf16 v[104:107], v[142:145], v[188:191], v[104:107]
	v_mfma_f32_16x16x32_bf16 v[112:115], v[156:159], v[188:191], v[112:115]
	v_mfma_f32_16x16x32_bf16 v[88:91], v[142:145], v[202:205], v[88:91]
	v_mfma_f32_16x16x32_bf16 v[96:99], v[156:159], v[202:205], v[96:99]
	v_mfma_f32_16x16x32_bf16 v[72:75], v[142:145], v[210:213], v[72:75]
	v_mfma_f32_16x16x32_bf16 v[80:83], v[156:159], v[210:213], v[80:83]
	v_mfma_f32_16x16x32_bf16 v[120:123], v[152:155], v[184:187], v[120:123]
	v_mfma_f32_16x16x32_bf16 v[128:131], v[160:163], v[184:187], v[128:131]
	v_mfma_f32_16x16x32_bf16 v[104:107], v[152:155], v[198:201], v[104:107]
	v_mfma_f32_16x16x32_bf16 v[112:115], v[160:163], v[198:201], v[112:115]
	v_mfma_f32_16x16x32_bf16 v[88:91], v[152:155], v[206:209], v[88:91]
	v_mfma_f32_16x16x32_bf16 v[96:99], v[160:163], v[206:209], v[96:99]
	v_mfma_f32_16x16x32_bf16 v[72:75], v[152:155], v[214:217], v[72:75]
	v_mfma_f32_16x16x32_bf16 v[80:83], v[160:163], v[214:217], v[80:83]
	s_setprio 0
	s_setprio 1
	v_mfma_f32_16x16x32_bf16 v[116:119], v[164:167], v[180:183], v[116:119]
	v_mfma_f32_16x16x32_bf16 v[124:127], v[172:175], v[180:183], v[124:127]
	v_mfma_f32_16x16x32_bf16 v[100:103], v[164:167], v[188:191], v[100:103]
	v_mfma_f32_16x16x32_bf16 v[108:111], v[172:175], v[188:191], v[108:111]
	v_mfma_f32_16x16x32_bf16 v[84:87], v[164:167], v[202:205], v[84:87]
	v_mfma_f32_16x16x32_bf16 v[92:95], v[172:175], v[202:205], v[92:95]
	v_mfma_f32_16x16x32_bf16 v[68:71], v[164:167], v[210:213], v[68:71]
	v_mfma_f32_16x16x32_bf16 v[76:79], v[172:175], v[210:213], v[76:79]
	v_mfma_f32_16x16x32_bf16 v[116:119], v[168:171], v[184:187], v[116:119]
	v_mfma_f32_16x16x32_bf16 v[124:127], v[176:179], v[184:187], v[124:127]
	v_mfma_f32_16x16x32_bf16 v[100:103], v[168:171], v[198:201], v[100:103]
	v_mfma_f32_16x16x32_bf16 v[108:111], v[176:179], v[198:201], v[108:111]
	v_mfma_f32_16x16x32_bf16 v[84:87], v[168:171], v[206:209], v[84:87]
	v_mfma_f32_16x16x32_bf16 v[92:95], v[176:179], v[206:209], v[92:95]
	v_mfma_f32_16x16x32_bf16 v[68:71], v[168:171], v[214:217], v[68:71]
	v_mfma_f32_16x16x32_bf16 v[76:79], v[176:179], v[214:217], v[76:79]
	s_setprio 0
	s_barrier
	s_add_i32 s50, s50, s22
	s_mov_b32 m0, s50
	ds_read_b128 v[180:183], v150 offset:16384
	ds_read_b128 v[184:187], v150 offset:17408
	ds_read_b128 v[188:191], v150 offset:18432
	ds_read_b128 v[198:201], v150 offset:19456
	ds_read_b128 v[202:205], v150 offset:20480
	ds_read_b128 v[206:209], v150 offset:21504
	ds_read_b128 v[210:213], v150 offset:22528
	ds_read_b128 v[214:217], v150 offset:23552
	global_load_lds_dwordx4 v2, s[48:49]
	s_add_i32 m0, s50, 0x2000
	s_add_i32 s47, s47, s22
	global_load_lds_dwordx4 v136, s[48:49]
	s_add_u32 s48, s48, s2
	s_addc_u32 s49, s49, s3
	s_mov_b64 vcc, s[48:49]
	s_sub_u32 s98, s48, s2
	s_subb_u32 s99, s49, s3
	s_mov_b32 m0, s47
	s_nop 0
	global_load_lds_dwordx4 v2, s[48:49]
	s_add_i32 m0, s47, 0x2000
	s_nop 0
	global_load_lds_dwordx4 v136, s[48:49]
	s_mov_b32 m0, s23
	s_nop 0
	global_load_lds_dwordx4 v132, s[18:19]
	s_mov_b32 m0, s24
	s_nop 0
	global_load_lds_dwordx4 v134, s[18:19]
	s_waitcnt vmcnt(8)
	s_waitcnt lgkmcnt(0)
	s_barrier
	s_setprio 1
	v_mfma_f32_16x16x32_bf16 v[56:59], v[142:145], v[180:183], v[56:59]
	v_mfma_f32_16x16x32_bf16 v[64:67], v[156:159], v[180:183], v[64:67]
	v_mfma_f32_16x16x32_bf16 v[40:43], v[142:145], v[188:191], v[40:43]
	v_mfma_f32_16x16x32_bf16 v[48:51], v[156:159], v[188:191], v[48:51]
	v_mfma_f32_16x16x32_bf16 v[24:27], v[142:145], v[202:205], v[24:27]
	v_mfma_f32_16x16x32_bf16 v[32:35], v[156:159], v[202:205], v[32:35]
	v_mfma_f32_16x16x32_bf16 v[8:11], v[142:145], v[210:213], v[8:11]
	v_mfma_f32_16x16x32_bf16 v[16:19], v[156:159], v[210:213], v[16:19]
	v_mfma_f32_16x16x32_bf16 v[56:59], v[152:155], v[184:187], v[56:59]
	v_mfma_f32_16x16x32_bf16 v[64:67], v[160:163], v[184:187], v[64:67]
	v_mfma_f32_16x16x32_bf16 v[40:43], v[152:155], v[198:201], v[40:43]
	v_mfma_f32_16x16x32_bf16 v[48:51], v[160:163], v[198:201], v[48:51]
	v_mfma_f32_16x16x32_bf16 v[24:27], v[152:155], v[206:209], v[24:27]
	v_mfma_f32_16x16x32_bf16 v[32:35], v[160:163], v[206:209], v[32:35]
	v_mfma_f32_16x16x32_bf16 v[8:11], v[152:155], v[214:217], v[8:11]
	v_mfma_f32_16x16x32_bf16 v[16:19], v[160:163], v[214:217], v[16:19]
	s_setprio 0
	s_setprio 1
	v_mfma_f32_16x16x32_bf16 v[52:55], v[164:167], v[180:183], v[52:55]
	v_mfma_f32_16x16x32_bf16 v[60:63], v[172:175], v[180:183], v[60:63]
	v_mfma_f32_16x16x32_bf16 v[36:39], v[164:167], v[188:191], v[36:39]
	v_mfma_f32_16x16x32_bf16 v[44:47], v[172:175], v[188:191], v[44:47]
	v_mfma_f32_16x16x32_bf16 v[20:23], v[164:167], v[202:205], v[20:23]
	v_mfma_f32_16x16x32_bf16 v[28:31], v[172:175], v[202:205], v[28:31]
	v_mfma_f32_16x16x32_bf16 v[4:7], v[164:167], v[210:213], v[4:7]
	v_mfma_f32_16x16x32_bf16 v[12:15], v[172:175], v[210:213], v[12:15]
	v_mfma_f32_16x16x32_bf16 v[52:55], v[168:171], v[184:187], v[52:55]
	v_mfma_f32_16x16x32_bf16 v[60:63], v[176:179], v[184:187], v[60:63]
	v_mfma_f32_16x16x32_bf16 v[36:39], v[168:171], v[198:201], v[36:39]
	v_mfma_f32_16x16x32_bf16 v[44:47], v[176:179], v[198:201], v[44:47]
	v_mfma_f32_16x16x32_bf16 v[20:23], v[168:171], v[206:209], v[20:23]
	v_mfma_f32_16x16x32_bf16 v[28:31], v[176:179], v[206:209], v[28:31]
	v_mfma_f32_16x16x32_bf16 v[4:7], v[168:171], v[214:217], v[4:7]
	v_mfma_f32_16x16x32_bf16 v[12:15], v[176:179], v[214:217], v[12:15]
	s_setprio 0
	s_barrier
; #define PG8_STAGE(bufoff, gbase, voff) do { _Pragma("unroll") for (int _i = 0; _i < 2; ++_i) \
;         __builtin_amdgcn_global_load_lds((const unsigned*)((const char*)(gbase) + (voff)[_i]), (PG8_LAS unsigned*)(lds + (bufoff) + ldsw + _i * 8192), 16, 0, 0); } while (0)
; #define PG8_LDA(dst, b, h) do { _Pragma("unroll") for (int m = 0; m < 4; ++m) _Pragma("unroll") for (int k = 0; k < 2; ++k) dst[m][k] = *(const PG8_LAS bf16x8*)(lds + PG8_SA(b, h) + aoff + m * 2048 + k * 1024); } while (0)
; #define PG8_LDB(dst, b, h) do { _Pragma("unroll") for (int n = 0; n < 2; ++n) _Pragma("unroll") for (int k = 0; k < 2; ++k) dst[n][k] = *(const PG8_LAS bf16x8*)(lds + PG8_SB(b, h) + boff + n * 2048 + k * 1024); } while (0)
; #define PG8_MMA(ai, bj, At, Bt) do { __builtin_amdgcn_s_setprio(1); _Pragma("unroll") for (int m = 0; m < 4; ++m) _Pragma("unroll") for (int n = 0; n < 2; ++n) _Pragma("unroll") for (int k = 0; k < 2; ++k) \
;         acc[ai][bj][m][n] = __builtin_amdgcn_mfma_f32_16x16x32_bf16(Bt[n][k], At[m][k], acc[ai][bj][m][n], 0, 0, 0); __builtin_amdgcn_s_setprio(0); } while (0)
; #define PG8_WAIT_V(n) asm volatile("s_waitcnt vmcnt(" #n ")" ::: "memory")
; #define PG8_WAIT_L(n) asm volatile("s_waitcnt lgkmcnt(" #n ")" ::: "memory")
; #define PG8_BAR __builtin_amdgcn_s_barrier()
; #define PG8_SCHED __builtin_amdgcn_sched_barrier(0)
; template <class Epi, class Sched, bool ALIGN_EPI = false, bool SP2 = false, bool ACHUNK = false>
; __device__ __forceinline__ void gemm_phase(PG8_LAS unsigned char* lds, const Gemm g, const Sched& S, const Epi& E) {
;     ...
;             PG8_LDB(B0, 1, 0); PG8_LDB(B1, 1, 1); PG8_SCHED; PG8_LDA(At, 1, 0); PG8_STAGE(PG8_SA(0, 1), a2 + hstepA, voffA);
;             PG8_WAIT_V(8); PG8_WAIT_L(0); PG8_BAR; PG8_MMA(0, 0, At, B0); PG8_MMA(0, 1, At, B1); PG8_BAR; PG8_SCHED;
;             PG8_LDA(At, 1, 1); PG8_STAGE(PG8_SB(1, 0), b3, voffB); PG8_STAGE(PG8_SB(1, 1), b3 + hstepB, voffB); PG8_STAGE(PG8_SA(1, 0), a3, voffA);
;             PG8_WAIT_V(8); PG8_WAIT_L(0); PG8_BAR; PG8_MMA(1, 0, At, B0); PG8_MMA(1, 1, At, B1); PG8_BAR; PG8_SCHED;
	s_add_i32 s47, 0, 0x18000
	v_add_u32_e32 v151, s47, v147
	s_add_i32 s48, 0, 0x1c000
	ds_read_b128 v[142:145], v151
	ds_read_b128 v[152:155], v151 offset:1024
	ds_read_b128 v[156:159], v151 offset:2048
	ds_read_b128 v[160:163], v151 offset:3072
	v_add_u32_e32 v151, s48, v147
	ds_read_b128 v[164:167], v151
	ds_read_b128 v[168:171], v151 offset:1024
	ds_read_b128 v[172:175], v151 offset:2048
	ds_read_b128 v[176:179], v151 offset:3072
	s_add_u32 s18, s18, s2
	s_addc_u32 s19, s19, s3
	s_mov_b32 m0, s25
	ds_read_b128 v[180:183], v150 offset:32768
	ds_read_b128 v[184:187], v150 offset:33792
	ds_read_b128 v[188:191], v150 offset:34816
	ds_read_b128 v[198:201], v150 offset:35840
	ds_read_b128 v[202:205], v150 offset:36864
	ds_read_b128 v[206:209], v150 offset:37888
	ds_read_b128 v[210:213], v150 offset:38912
	ds_read_b128 v[214:217], v150 offset:39936
	global_load_lds_dwordx4 v132, s[18:19]
	s_mov_b32 m0, s26
	s_nop 0
	global_load_lds_dwordx4 v134, s[18:19]
	s_waitcnt vmcnt(8)
	s_waitcnt lgkmcnt(0)
	s_barrier
	s_setprio 1
	v_mfma_f32_16x16x32_bf16 v[120:123], v[142:145], v[180:183], v[120:123]
	v_mfma_f32_16x16x32_bf16 v[128:131], v[156:159], v[180:183], v[128:131]
	v_mfma_f32_16x16x32_bf16 v[104:107], v[142:145], v[188:191], v[104:107]
	v_mfma_f32_16x16x32_bf16 v[112:115], v[156:159], v[188:191], v[112:115]
	v_mfma_f32_16x16x32_bf16 v[88:91], v[142:145], v[202:205], v[88:91]
	v_mfma_f32_16x16x32_bf16 v[96:99], v[156:159], v[202:205], v[96:99]
	v_mfma_f32_16x16x32_bf16 v[72:75], v[142:145], v[210:213], v[72:75]
	v_mfma_f32_16x16x32_bf16 v[80:83], v[156:159], v[210:213], v[80:83]
	v_mfma_f32_16x16x32_bf16 v[120:123], v[152:155], v[184:187], v[120:123]
	v_mfma_f32_16x16x32_bf16 v[128:131], v[160:163], v[184:187], v[128:131]
	v_mfma_f32_16x16x32_bf16 v[104:107], v[152:155], v[198:201], v[104:107]
	v_mfma_f32_16x16x32_bf16 v[112:115], v[160:163], v[198:201], v[112:115]
	v_mfma_f32_16x16x32_bf16 v[88:91], v[152:155], v[206:209], v[88:91]
	v_mfma_f32_16x16x32_bf16 v[96:99], v[160:163], v[206:209], v[96:99]
	v_mfma_f32_16x16x32_bf16 v[72:75], v[152:155], v[214:217], v[72:75]
	v_mfma_f32_16x16x32_bf16 v[80:83], v[160:163], v[214:217], v[80:83]
	s_setprio 0
	s_setprio 1
	v_mfma_f32_16x16x32_bf16 v[116:119], v[164:167], v[180:183], v[116:119]
	v_mfma_f32_16x16x32_bf16 v[124:127], v[172:175], v[180:183], v[124:127]
	v_mfma_f32_16x16x32_bf16 v[100:103], v[164:167], v[188:191], v[100:103]
	v_mfma_f32_16x16x32_bf16 v[108:111], v[172:175], v[188:191], v[108:111]
	v_mfma_f32_16x16x32_bf16 v[84:87], v[164:167], v[202:205], v[84:87]
	v_mfma_f32_16x16x32_bf16 v[92:95], v[172:175], v[202:205], v[92:95]
	v_mfma_f32_16x16x32_bf16 v[68:71], v[164:167], v[210:213], v[68:71]
	v_mfma_f32_16x16x32_bf16 v[76:79], v[172:175], v[210:213], v[76:79]
	v_mfma_f32_16x16x32_bf16 v[116:119], v[168:171], v[184:187], v[116:119]
	v_mfma_f32_16x16x32_bf16 v[124:127], v[176:179], v[184:187], v[124:127]
	v_mfma_f32_16x16x32_bf16 v[100:103], v[168:171], v[198:201], v[100:103]
	v_mfma_f32_16x16x32_bf16 v[108:111], v[176:179], v[198:201], v[108:111]
	v_mfma_f32_16x16x32_bf16 v[84:87], v[168:171], v[206:209], v[84:87]
	v_mfma_f32_16x16x32_bf16 v[92:95], v[176:179], v[206:209], v[92:95]
	v_mfma_f32_16x16x32_bf16 v[68:71], v[168:171], v[214:217], v[68:71]
	v_mfma_f32_16x16x32_bf16 v[76:79], v[176:179], v[214:217], v[76:79]
	s_setprio 0
	s_barrier
	s_add_u32 vcc_lo, vcc_lo, s10
	s_addc_u32 vcc_hi, vcc_hi, s11
	s_add_u32 s98, s98, s10
	s_addc_u32 s99, s99, s11
	s_sub_u32 s18, s18, s2
	s_subb_u32 s19, s19, s3
	s_add_u32 s18, s18, s10
	s_addc_u32 s19, s19, s11
	s_add_i32 m0, s47, s22
	ds_read_b128 v[180:183], v150 offset:49152
	ds_read_b128 v[184:187], v150 offset:50176
	ds_read_b128 v[188:191], v150 offset:51200
	ds_read_b128 v[198:201], v150 offset:52224
	ds_read_b128 v[202:205], v150 offset:53248
	ds_read_b128 v[206:209], v150 offset:54272
	ds_read_b128 v[210:213], v150 offset:55296
	ds_read_b128 v[214:217], v150 offset:56320
	global_load_lds_dwordx4 v2, s[98:99]
	s_add_i32 m0, m0, 0x2000
	s_nop 0
	global_load_lds_dwordx4 v136, s[98:99]
	s_add_i32 m0, s48, s22
	s_nop 0
	global_load_lds_dwordx4 v2, vcc
	s_add_i32 m0, m0, 0x2000
	s_nop 0
	global_load_lds_dwordx4 v136, vcc
	s_mov_b32 m0, s27
	s_nop 0
	global_load_lds_dwordx4 v132, s[18:19]
	s_mov_b32 m0, s28
	s_nop 0
	global_load_lds_dwordx4 v134, s[18:19]
	s_waitcnt vmcnt(8)
	s_waitcnt lgkmcnt(0)
	s_barrier
	s_setprio 1
	v_mfma_f32_16x16x32_bf16 v[56:59], v[142:145], v[180:183], v[56:59]
	v_mfma_f32_16x16x32_bf16 v[64:67], v[156:159], v[180:183], v[64:67]
	v_mfma_f32_16x16x32_bf16 v[40:43], v[142:145], v[188:191], v[40:43]
	v_mfma_f32_16x16x32_bf16 v[48:51], v[156:159], v[188:191], v[48:51]
	v_mfma_f32_16x16x32_bf16 v[24:27], v[142:145], v[202:205], v[24:27]
	v_mfma_f32_16x16x32_bf16 v[32:35], v[156:159], v[202:205], v[32:35]
	v_mfma_f32_16x16x32_bf16 v[8:11], v[142:145], v[210:213], v[8:11]
	v_mfma_f32_16x16x32_bf16 v[16:19], v[156:159], v[210:213], v[16:19]
	v_mfma_f32_16x16x32_bf16 v[56:59], v[152:155], v[184:187], v[56:59]
	v_mfma_f32_16x16x32_bf16 v[64:67], v[160:163], v[184:187], v[64:67]
	v_mfma_f32_16x16x32_bf16 v[40:43], v[152:155], v[198:201], v[40:43]
	v_mfma_f32_16x16x32_bf16 v[48:51], v[160:163], v[198:201], v[48:51]
	v_mfma_f32_16x16x32_bf16 v[24:27], v[152:155], v[206:209], v[24:27]
	v_mfma_f32_16x16x32_bf16 v[32:35], v[160:163], v[206:209], v[32:35]
	v_mfma_f32_16x16x32_bf16 v[8:11], v[152:155], v[214:217], v[8:11]
	v_mfma_f32_16x16x32_bf16 v[16:19], v[160:163], v[214:217], v[16:19]
	s_setprio 0
	s_setprio 1
	v_mfma_f32_16x16x32_bf16 v[52:55], v[164:167], v[180:183], v[52:55]
	v_mfma_f32_16x16x32_bf16 v[60:63], v[172:175], v[180:183], v[60:63]
	v_mfma_f32_16x16x32_bf16 v[36:39], v[164:167], v[188:191], v[36:39]
	v_mfma_f32_16x16x32_bf16 v[44:47], v[172:175], v[188:191], v[44:47]
	v_mfma_f32_16x16x32_bf16 v[20:23], v[164:167], v[202:205], v[20:23]
	v_mfma_f32_16x16x32_bf16 v[28:31], v[172:175], v[202:205], v[28:31]
	v_mfma_f32_16x16x32_bf16 v[4:7], v[164:167], v[210:213], v[4:7]
	v_mfma_f32_16x16x32_bf16 v[12:15], v[172:175], v[210:213], v[12:15]
	v_mfma_f32_16x16x32_bf16 v[52:55], v[168:171], v[184:187], v[52:55]
	v_mfma_f32_16x16x32_bf16 v[60:63], v[176:179], v[184:187], v[60:63]
	v_mfma_f32_16x16x32_bf16 v[36:39], v[168:171], v[198:201], v[36:39]
	v_mfma_f32_16x16x32_bf16 v[44:47], v[176:179], v[198:201], v[44:47]
	v_mfma_f32_16x16x32_bf16 v[20:23], v[168:171], v[206:209], v[20:23]
	v_mfma_f32_16x16x32_bf16 v[28:31], v[176:179], v[206:209], v[28:31]
	v_mfma_f32_16x16x32_bf16 v[4:7], v[168:171], v[214:217], v[4:7]
	v_mfma_f32_16x16x32_bf16 v[12:15], v[176:179], v[214:217], v[12:15]
	s_setprio 0
	s_barrier
	s_add_u32 s20, s20, 0x100
	s_addc_u32 s21, s21, 0
	s_add_u32 s44, s44, 0x100
	s_addc_u32 s45, s45, 0
	s_cmp_ge_i32 s46, s29
	s_mov_b32 s18, s46
	s_cbranch_scc0 .LBB0_52
	v_readlane_b32 s47, v255, 0
	s_mov_b32 s50, s94
	s_and_b64 vcc, exec, s[12:13]
	s_cbranch_vccnz .LBB0_57
	s_branch .LBB0_58

; #define PG8_STAGE(bufoff, gbase, voff) do { _Pragma("unroll") for (int _i = 0; _i < 2; ++_i) \
;         __builtin_amdgcn_global_load_lds((const unsigned*)((const char*)(gbase) + (voff)[_i]), (PG8_LAS unsigned*)(lds + (bufoff) + ldsw + _i * 8192), 16, 0, 0); } while (0)
; #define PG8_LDA(dst, b, h) do { _Pragma("unroll") for (int m = 0; m < 4; ++m) _Pragma("unroll") for (int k = 0; k < 2; ++k) dst[m][k] = *(const PG8_LAS bf16x8*)(lds + PG8_SA(b, h) + aoff + m * 2048 + k * 1024); } while (0)
; #define PG8_LDB(dst, b, h) do { _Pragma("unroll") for (int n = 0; n < 2; ++n) _Pragma("unroll") for (int k = 0; k < 2; ++k) dst[n][k] = *(const PG8_LAS bf16x8*)(lds + PG8_SB(b, h) + boff + n * 2048 + k * 1024); } while (0)
; #define PG8_MMA(ai, bj, At, Bt) do { __builtin_amdgcn_s_setprio(1); _Pragma("unroll") for (int m = 0; m < 4; ++m) _Pragma("unroll") for (int n = 0; n < 2; ++n) _Pragma("unroll") for (int k = 0; k < 2; ++k) \
;         acc[ai][bj][m][n] = __builtin_amdgcn_mfma_f32_16x16x32_bf16(Bt[n][k], At[m][k], acc[ai][bj][m][n], 0, 0, 0); __builtin_amdgcn_s_setprio(0); } while (0)
; #define PG8_WAIT_V(n) asm volatile("s_waitcnt vmcnt(" #n ")" ::: "memory")
; #define PG8_WAIT_L(n) asm volatile("s_waitcnt lgkmcnt(" #n ")" ::: "memory")
; #define PG8_BAR __builtin_amdgcn_s_barrier()
; #define PG8_SCHED __builtin_amdgcn_sched_barrier(0)
; template <class Epi, class Sched, bool ALIGN_EPI = false, bool SP2 = false, bool ACHUNK = false>
; __device__ __forceinline__ void gemm_phase(PG8_LAS unsigned char* lds, const Gemm g, const Sched& S, const Epi& E) {
;     ...
;             PG8_LDB(B0, 0, 0); PG8_LDB(B1, 0, 1); PG8_SCHED; PG8_LDA(At, 0, 0); PG8_STAGE(PG8_SA(1, 1), a1 + hstepA, voffA);
;             PG8_WAIT_V(8); PG8_WAIT_L(0); PG8_BAR; PG8_MMA(0, 0, At, B0); PG8_MMA(0, 1, At, B1); PG8_BAR; PG8_SCHED;
;             PG8_LDA(At, 0, 1); PG8_STAGE(PG8_SB(0, 0), b2, voffB); PG8_STAGE(PG8_SB(0, 1), b2 + hstepB, voffB); PG8_STAGE(PG8_SA(0, 0), a2, voffA);
;             PG8_WAIT_V(8); PG8_WAIT_L(0); PG8_BAR; PG8_MMA(1, 0, At, B0); PG8_MMA(1, 1, At, B1); PG8_BAR; PG8_SCHED;
.Lnl_wo:
	s_add_i32 s51, 0, 0x14000
	ds_read_b128 v[142:145], v151
	ds_read_b128 v[152:155], v151 offset:1024
	ds_read_b128 v[156:159], v151 offset:2048
	ds_read_b128 v[160:163], v151 offset:3072
	v_add_u32_e32 v151, s51, v147
	ds_read_b128 v[164:167], v151
	ds_read_b128 v[168:171], v151 offset:1024
	ds_read_b128 v[172:175], v151 offset:2048
	ds_read_b128 v[176:179], v151 offset:3072
	s_add_i32 m0, s27, 0xc000
	ds_read_b128 v[180:183], v149
	ds_read_b128 v[184:187], v149 offset:1024
	ds_read_b128 v[188:191], v149 offset:2048
	ds_read_b128 v[198:201], v149 offset:3072
	ds_read_b128 v[202:205], v149 offset:4096
	ds_read_b128 v[206:209], v149 offset:5120
	ds_read_b128 v[210:213], v149 offset:6144
	ds_read_b128 v[214:217], v149 offset:7168
	global_load_lds_dwordx4 v138, s[20:21]
	s_add_i32 m0, s27, 0xe000
	s_nop 0
	global_load_lds_dwordx4 v140, s[20:21]
	s_waitcnt vmcnt(8)
	s_waitcnt lgkmcnt(0)
	s_barrier
	s_setprio 1
	v_mfma_f32_16x16x32_bf16 v[120:123], v[142:145], v[180:183], v[120:123]
	v_mfma_f32_16x16x32_bf16 v[128:131], v[156:159], v[180:183], v[128:131]
	v_mfma_f32_16x16x32_bf16 v[104:107], v[142:145], v[188:191], v[104:107]
	v_mfma_f32_16x16x32_bf16 v[112:115], v[156:159], v[188:191], v[112:115]
	v_mfma_f32_16x16x32_bf16 v[88:91], v[142:145], v[202:205], v[88:91]
	v_mfma_f32_16x16x32_bf16 v[96:99], v[156:159], v[202:205], v[96:99]
	v_mfma_f32_16x16x32_bf16 v[72:75], v[142:145], v[210:213], v[72:75]
	v_mfma_f32_16x16x32_bf16 v[80:83], v[156:159], v[210:213], v[80:83]
	v_mfma_f32_16x16x32_bf16 v[120:123], v[152:155], v[184:187], v[120:123]
	v_mfma_f32_16x16x32_bf16 v[128:131], v[160:163], v[184:187], v[128:131]
	v_mfma_f32_16x16x32_bf16 v[104:107], v[152:155], v[198:201], v[104:107]
	v_mfma_f32_16x16x32_bf16 v[112:115], v[160:163], v[198:201], v[112:115]
	v_mfma_f32_16x16x32_bf16 v[88:91], v[152:155], v[206:209], v[88:91]
	v_mfma_f32_16x16x32_bf16 v[96:99], v[160:163], v[206:209], v[96:99]
	v_mfma_f32_16x16x32_bf16 v[72:75], v[152:155], v[214:217], v[72:75]
	v_mfma_f32_16x16x32_bf16 v[80:83], v[160:163], v[214:217], v[80:83]
	s_setprio 0
	s_setprio 1
	v_mfma_f32_16x16x32_bf16 v[116:119], v[164:167], v[180:183], v[116:119]
	v_mfma_f32_16x16x32_bf16 v[124:127], v[172:175], v[180:183], v[124:127]
	v_mfma_f32_16x16x32_bf16 v[100:103], v[164:167], v[188:191], v[100:103]
	v_mfma_f32_16x16x32_bf16 v[108:111], v[172:175], v[188:191], v[108:111]
	v_mfma_f32_16x16x32_bf16 v[84:87], v[164:167], v[202:205], v[84:87]
	v_mfma_f32_16x16x32_bf16 v[92:95], v[172:175], v[202:205], v[92:95]
	v_mfma_f32_16x16x32_bf16 v[68:71], v[164:167], v[210:213], v[68:71]
	v_mfma_f32_16x16x32_bf16 v[76:79], v[172:175], v[210:213], v[76:79]
	v_mfma_f32_16x16x32_bf16 v[116:119], v[168:171], v[184:187], v[116:119]
	v_mfma_f32_16x16x32_bf16 v[124:127], v[176:179], v[184:187], v[124:127]
	v_mfma_f32_16x16x32_bf16 v[100:103], v[168:171], v[198:201], v[100:103]
	v_mfma_f32_16x16x32_bf16 v[108:111], v[176:179], v[198:201], v[108:111]
	v_mfma_f32_16x16x32_bf16 v[84:87], v[168:171], v[206:209], v[84:87]
	v_mfma_f32_16x16x32_bf16 v[92:95], v[176:179], v[206:209], v[92:95]
	v_mfma_f32_16x16x32_bf16 v[68:71], v[168:171], v[214:217], v[68:71]
	v_mfma_f32_16x16x32_bf16 v[76:79], v[176:179], v[214:217], v[76:79]
	s_setprio 0
	s_barrier
	s_add_i32 s54, s54, s26
	s_mov_b32 m0, s54
	ds_read_b128 v[180:183], v149 offset:16384
	ds_read_b128 v[184:187], v149 offset:17408
	ds_read_b128 v[188:191], v149 offset:18432
	ds_read_b128 v[198:201], v149 offset:19456
	ds_read_b128 v[202:205], v149 offset:20480
	ds_read_b128 v[206:209], v149 offset:21504
	ds_read_b128 v[210:213], v149 offset:22528
	ds_read_b128 v[214:217], v149 offset:23552
	global_load_lds_dwordx4 v2, s[52:53]
	s_add_i32 m0, s54, 0x2000
	s_add_i32 s51, s51, s26
	global_load_lds_dwordx4 v136, s[52:53]
	s_add_u32 s52, s52, s4
	s_addc_u32 s53, s53, s5
	s_mov_b64 vcc, s[52:53]
	s_sub_u32 s98, s52, s4
	s_subb_u32 s99, s53, s5
	s_mov_b32 m0, s51
	s_nop 0
	global_load_lds_dwordx4 v2, s[52:53]
	s_add_i32 m0, s51, 0x2000
	s_nop 0
	global_load_lds_dwordx4 v136, s[52:53]
	s_mov_b32 m0, s27
	s_nop 0
	global_load_lds_dwordx4 v132, s[22:23]
	s_mov_b32 m0, s28
	s_nop 0
	global_load_lds_dwordx4 v134, s[22:23]
	s_waitcnt vmcnt(8)
	s_waitcnt lgkmcnt(0)
	s_barrier
	s_setprio 1
	v_mfma_f32_16x16x32_bf16 v[56:59], v[142:145], v[180:183], v[56:59]
	v_mfma_f32_16x16x32_bf16 v[64:67], v[156:159], v[180:183], v[64:67]
	v_mfma_f32_16x16x32_bf16 v[40:43], v[142:145], v[188:191], v[40:43]
	v_mfma_f32_16x16x32_bf16 v[48:51], v[156:159], v[188:191], v[48:51]
	v_mfma_f32_16x16x32_bf16 v[24:27], v[142:145], v[202:205], v[24:27]
	v_mfma_f32_16x16x32_bf16 v[32:35], v[156:159], v[202:205], v[32:35]
	v_mfma_f32_16x16x32_bf16 v[8:11], v[142:145], v[210:213], v[8:11]
	v_mfma_f32_16x16x32_bf16 v[16:19], v[156:159], v[210:213], v[16:19]
	v_mfma_f32_16x16x32_bf16 v[56:59], v[152:155], v[184:187], v[56:59]
	v_mfma_f32_16x16x32_bf16 v[64:67], v[160:163], v[184:187], v[64:67]
	v_mfma_f32_16x16x32_bf16 v[40:43], v[152:155], v[198:201], v[40:43]
	v_mfma_f32_16x16x32_bf16 v[48:51], v[160:163], v[198:201], v[48:51]
	v_mfma_f32_16x16x32_bf16 v[24:27], v[152:155], v[206:209], v[24:27]
	v_mfma_f32_16x16x32_bf16 v[32:35], v[160:163], v[206:209], v[32:35]
	v_mfma_f32_16x16x32_bf16 v[8:11], v[152:155], v[214:217], v[8:11]
	v_mfma_f32_16x16x32_bf16 v[16:19], v[160:163], v[214:217], v[16:19]
	s_setprio 0
	s_setprio 1
	v_mfma_f32_16x16x32_bf16 v[52:55], v[164:167], v[180:183], v[52:55]
	v_mfma_f32_16x16x32_bf16 v[60:63], v[172:175], v[180:183], v[60:63]
	v_mfma_f32_16x16x32_bf16 v[36:39], v[164:167], v[188:191], v[36:39]
	v_mfma_f32_16x16x32_bf16 v[44:47], v[172:175], v[188:191], v[44:47]
	v_mfma_f32_16x16x32_bf16 v[20:23], v[164:167], v[202:205], v[20:23]
	v_mfma_f32_16x16x32_bf16 v[28:31], v[172:175], v[202:205], v[28:31]
	v_mfma_f32_16x16x32_bf16 v[4:7], v[164:167], v[210:213], v[4:7]
	v_mfma_f32_16x16x32_bf16 v[12:15], v[172:175], v[210:213], v[12:15]
	v_mfma_f32_16x16x32_bf16 v[52:55], v[168:171], v[184:187], v[52:55]
	v_mfma_f32_16x16x32_bf16 v[60:63], v[176:179], v[184:187], v[60:63]
	v_mfma_f32_16x16x32_bf16 v[36:39], v[168:171], v[198:201], v[36:39]
	v_mfma_f32_16x16x32_bf16 v[44:47], v[176:179], v[198:201], v[44:47]
	v_mfma_f32_16x16x32_bf16 v[20:23], v[168:171], v[206:209], v[20:23]
	v_mfma_f32_16x16x32_bf16 v[28:31], v[176:179], v[206:209], v[28:31]
	v_mfma_f32_16x16x32_bf16 v[4:7], v[168:171], v[214:217], v[4:7]
	v_mfma_f32_16x16x32_bf16 v[12:15], v[176:179], v[214:217], v[12:15]
	s_setprio 0
	s_barrier
; #define PG8_STAGE(bufoff, gbase, voff) do { _Pragma("unroll") for (int _i = 0; _i < 2; ++_i) \
;         __builtin_amdgcn_global_load_lds((const unsigned*)((const char*)(gbase) + (voff)[_i]), (PG8_LAS unsigned*)(lds + (bufoff) + ldsw + _i * 8192), 16, 0, 0); } while (0)
; #define PG8_LDA(dst, b, h) do { _Pragma("unroll") for (int m = 0; m < 4; ++m) _Pragma("unroll") for (int k = 0; k < 2; ++k) dst[m][k] = *(const PG8_LAS bf16x8*)(lds + PG8_SA(b, h) + aoff + m * 2048 + k * 1024); } while (0)
; #define PG8_LDB(dst, b, h) do { _Pragma("unroll") for (int n = 0; n < 2; ++n) _Pragma("unroll") for (int k = 0; k < 2; ++k) dst[n][k] = *(const PG8_LAS bf16x8*)(lds + PG8_SB(b, h) + boff + n * 2048 + k * 1024); } while (0)
; #define PG8_MMA(ai, bj, At, Bt) do { __builtin_amdgcn_s_setprio(1); _Pragma("unroll") for (int m = 0; m < 4; ++m) _Pragma("unroll") for (int n = 0; n < 2; ++n) _Pragma("unroll") for (int k = 0; k < 2; ++k) \
;         acc[ai][bj][m][n] = __builtin_amdgcn_mfma_f32_16x16x32_bf16(Bt[n][k], At[m][k], acc[ai][bj][m][n], 0, 0, 0); __builtin_amdgcn_s_setprio(0); } while (0)
; #define PG8_WAIT_V(n) asm volatile("s_waitcnt vmcnt(" #n ")" ::: "memory")
; #define PG8_WAIT_L(n) asm volatile("s_waitcnt lgkmcnt(" #n ")" ::: "memory")
; #define PG8_BAR __builtin_amdgcn_s_barrier()
; #define PG8_SCHED __builtin_amdgcn_sched_barrier(0)
; template <class Epi, class Sched, bool ALIGN_EPI = false, bool SP2 = false, bool ACHUNK = false>
; __device__ __forceinline__ void gemm_phase(PG8_LAS unsigned char* lds, const Gemm g, const Sched& S, const Epi& E) {
;     ...
;             PG8_LDB(B0, 1, 0); PG8_LDB(B1, 1, 1); PG8_SCHED; PG8_LDA(At, 1, 0); PG8_STAGE(PG8_SA(0, 1), a2 + hstepA, voffA);
;             PG8_WAIT_V(8); PG8_WAIT_L(0); PG8_BAR; PG8_MMA(0, 0, At, B0); PG8_MMA(0, 1, At, B1); PG8_BAR; PG8_SCHED;
;             PG8_LDA(At, 1, 1); PG8_STAGE(PG8_SB(1, 0), b3, voffB); PG8_STAGE(PG8_SB(1, 1), b3 + hstepB, voffB); PG8_STAGE(PG8_SA(1, 0), a3, voffA);
;             PG8_WAIT_V(8); PG8_WAIT_L(0); PG8_BAR; PG8_MMA(1, 0, At, B0); PG8_MMA(1, 1, At, B1); PG8_BAR; PG8_SCHED;
	s_add_i32 s51, 0, 0x18000
	v_add_u32_e32 v151, s51, v147
	s_add_i32 s52, 0, 0x1c000
	ds_read_b128 v[142:145], v151
	ds_read_b128 v[152:155], v151 offset:1024
	ds_read_b128 v[156:159], v151 offset:2048
	ds_read_b128 v[160:163], v151 offset:3072
	v_add_u32_e32 v151, s52, v147
	ds_read_b128 v[164:167], v151
	ds_read_b128 v[168:171], v151 offset:1024
	ds_read_b128 v[172:175], v151 offset:2048
	ds_read_b128 v[176:179], v151 offset:3072
	s_add_u32 s22, s22, s4
	s_addc_u32 s23, s23, s5
	s_mov_b32 m0, s29
	ds_read_b128 v[180:183], v149 offset:32768
	ds_read_b128 v[184:187], v149 offset:33792
	ds_read_b128 v[188:191], v149 offset:34816
	ds_read_b128 v[198:201], v149 offset:35840
	ds_read_b128 v[202:205], v149 offset:36864
	ds_read_b128 v[206:209], v149 offset:37888
	ds_read_b128 v[210:213], v149 offset:38912
	ds_read_b128 v[214:217], v149 offset:39936
	global_load_lds_dwordx4 v132, s[22:23]
	s_mov_b32 m0, s30
	s_nop 0
	global_load_lds_dwordx4 v134, s[22:23]
	s_waitcnt vmcnt(8)
	s_waitcnt lgkmcnt(0)
	s_barrier
	s_setprio 1
	v_mfma_f32_16x16x32_bf16 v[120:123], v[142:145], v[180:183], v[120:123]
	v_mfma_f32_16x16x32_bf16 v[128:131], v[156:159], v[180:183], v[128:131]
	v_mfma_f32_16x16x32_bf16 v[104:107], v[142:145], v[188:191], v[104:107]
	v_mfma_f32_16x16x32_bf16 v[112:115], v[156:159], v[188:191], v[112:115]
	v_mfma_f32_16x16x32_bf16 v[88:91], v[142:145], v[202:205], v[88:91]
	v_mfma_f32_16x16x32_bf16 v[96:99], v[156:159], v[202:205], v[96:99]
	v_mfma_f32_16x16x32_bf16 v[72:75], v[142:145], v[210:213], v[72:75]
	v_mfma_f32_16x16x32_bf16 v[80:83], v[156:159], v[210:213], v[80:83]
	v_mfma_f32_16x16x32_bf16 v[120:123], v[152:155], v[184:187], v[120:123]
	v_mfma_f32_16x16x32_bf16 v[128:131], v[160:163], v[184:187], v[128:131]
	v_mfma_f32_16x16x32_bf16 v[104:107], v[152:155], v[198:201], v[104:107]
	v_mfma_f32_16x16x32_bf16 v[112:115], v[160:163], v[198:201], v[112:115]
	v_mfma_f32_16x16x32_bf16 v[88:91], v[152:155], v[206:209], v[88:91]
	v_mfma_f32_16x16x32_bf16 v[96:99], v[160:163], v[206:209], v[96:99]
	v_mfma_f32_16x16x32_bf16 v[72:75], v[152:155], v[214:217], v[72:75]
	v_mfma_f32_16x16x32_bf16 v[80:83], v[160:163], v[214:217], v[80:83]
	s_setprio 0
	s_setprio 1
	v_mfma_f32_16x16x32_bf16 v[116:119], v[164:167], v[180:183], v[116:119]
	v_mfma_f32_16x16x32_bf16 v[124:127], v[172:175], v[180:183], v[124:127]
	v_mfma_f32_16x16x32_bf16 v[100:103], v[164:167], v[188:191], v[100:103]
	v_mfma_f32_16x16x32_bf16 v[108:111], v[172:175], v[188:191], v[108:111]
	v_mfma_f32_16x16x32_bf16 v[84:87], v[164:167], v[202:205], v[84:87]
	v_mfma_f32_16x16x32_bf16 v[92:95], v[172:175], v[202:205], v[92:95]
	v_mfma_f32_16x16x32_bf16 v[68:71], v[164:167], v[210:213], v[68:71]
	v_mfma_f32_16x16x32_bf16 v[76:79], v[172:175], v[210:213], v[76:79]
	v_mfma_f32_16x16x32_bf16 v[116:119], v[168:171], v[184:187], v[116:119]
	v_mfma_f32_16x16x32_bf16 v[124:127], v[176:179], v[184:187], v[124:127]
	v_mfma_f32_16x16x32_bf16 v[100:103], v[168:171], v[198:201], v[100:103]
	v_mfma_f32_16x16x32_bf16 v[108:111], v[176:179], v[198:201], v[108:111]
	v_mfma_f32_16x16x32_bf16 v[84:87], v[168:171], v[206:209], v[84:87]
	v_mfma_f32_16x16x32_bf16 v[92:95], v[176:179], v[206:209], v[92:95]
	v_mfma_f32_16x16x32_bf16 v[68:71], v[168:171], v[214:217], v[68:71]
	v_mfma_f32_16x16x32_bf16 v[76:79], v[176:179], v[214:217], v[76:79]
	s_setprio 0
	s_barrier
	s_add_u32 vcc_lo, vcc_lo, s10
	s_addc_u32 vcc_hi, vcc_hi, s11
	s_add_u32 s98, s98, s10
	s_addc_u32 s99, s99, s11
	s_sub_u32 s22, s22, s4
	s_subb_u32 s23, s23, s5
	s_add_u32 s22, s22, s10
	s_addc_u32 s23, s23, s11
	s_add_i32 m0, s51, s26
	ds_read_b128 v[180:183], v149 offset:49152
	ds_read_b128 v[184:187], v149 offset:50176
	ds_read_b128 v[188:191], v149 offset:51200
	ds_read_b128 v[198:201], v149 offset:52224
	ds_read_b128 v[202:205], v149 offset:53248
	ds_read_b128 v[206:209], v149 offset:54272
	ds_read_b128 v[210:213], v149 offset:55296
	ds_read_b128 v[214:217], v149 offset:56320
	global_load_lds_dwordx4 v2, s[98:99]
	s_add_i32 m0, m0, 0x2000
	s_nop 0
	global_load_lds_dwordx4 v136, s[98:99]
	s_add_i32 m0, s52, s26
	s_nop 0
	global_load_lds_dwordx4 v2, vcc
	s_add_i32 m0, m0, 0x2000
	s_nop 0
	global_load_lds_dwordx4 v136, vcc
	s_mov_b32 m0, s31
	s_nop 0
	global_load_lds_dwordx4 v132, s[22:23]
	s_mov_b32 m0, s33
	s_nop 0
	global_load_lds_dwordx4 v134, s[22:23]
	s_waitcnt vmcnt(8)
	s_waitcnt lgkmcnt(0)
	s_barrier
	s_setprio 1
	v_mfma_f32_16x16x32_bf16 v[56:59], v[142:145], v[180:183], v[56:59]
	v_mfma_f32_16x16x32_bf16 v[64:67], v[156:159], v[180:183], v[64:67]
	v_mfma_f32_16x16x32_bf16 v[40:43], v[142:145], v[188:191], v[40:43]
	v_mfma_f32_16x16x32_bf16 v[48:51], v[156:159], v[188:191], v[48:51]
	v_mfma_f32_16x16x32_bf16 v[24:27], v[142:145], v[202:205], v[24:27]
	v_mfma_f32_16x16x32_bf16 v[32:35], v[156:159], v[202:205], v[32:35]
	v_mfma_f32_16x16x32_bf16 v[8:11], v[142:145], v[210:213], v[8:11]
	v_mfma_f32_16x16x32_bf16 v[16:19], v[156:159], v[210:213], v[16:19]
	v_mfma_f32_16x16x32_bf16 v[56:59], v[152:155], v[184:187], v[56:59]
	v_mfma_f32_16x16x32_bf16 v[64:67], v[160:163], v[184:187], v[64:67]
	v_mfma_f32_16x16x32_bf16 v[40:43], v[152:155], v[198:201], v[40:43]
	v_mfma_f32_16x16x32_bf16 v[48:51], v[160:163], v[198:201], v[48:51]
	v_mfma_f32_16x16x32_bf16 v[24:27], v[152:155], v[206:209], v[24:27]
	v_mfma_f32_16x16x32_bf16 v[32:35], v[160:163], v[206:209], v[32:35]
	v_mfma_f32_16x16x32_bf16 v[8:11], v[152:155], v[214:217], v[8:11]
	v_mfma_f32_16x16x32_bf16 v[16:19], v[160:163], v[214:217], v[16:19]
	s_setprio 0
	s_setprio 1
	v_mfma_f32_16x16x32_bf16 v[52:55], v[164:167], v[180:183], v[52:55]
	v_mfma_f32_16x16x32_bf16 v[60:63], v[172:175], v[180:183], v[60:63]
	v_mfma_f32_16x16x32_bf16 v[36:39], v[164:167], v[188:191], v[36:39]
	v_mfma_f32_16x16x32_bf16 v[44:47], v[172:175], v[188:191], v[44:47]
	v_mfma_f32_16x16x32_bf16 v[20:23], v[164:167], v[202:205], v[20:23]
	v_mfma_f32_16x16x32_bf16 v[28:31], v[172:175], v[202:205], v[28:31]
	v_mfma_f32_16x16x32_bf16 v[4:7], v[164:167], v[210:213], v[4:7]
	v_mfma_f32_16x16x32_bf16 v[12:15], v[172:175], v[210:213], v[12:15]
	v_mfma_f32_16x16x32_bf16 v[52:55], v[168:171], v[184:187], v[52:55]
	v_mfma_f32_16x16x32_bf16 v[60:63], v[176:179], v[184:187], v[60:63]
	v_mfma_f32_16x16x32_bf16 v[36:39], v[168:171], v[198:201], v[36:39]
	v_mfma_f32_16x16x32_bf16 v[44:47], v[176:179], v[198:201], v[44:47]
	v_mfma_f32_16x16x32_bf16 v[20:23], v[168:171], v[206:209], v[20:23]
	v_mfma_f32_16x16x32_bf16 v[28:31], v[176:179], v[206:209], v[28:31]
	v_mfma_f32_16x16x32_bf16 v[4:7], v[168:171], v[214:217], v[4:7]
	v_mfma_f32_16x16x32_bf16 v[12:15], v[176:179], v[214:217], v[12:15]
	s_setprio 0
	s_barrier
	s_add_u32 s48, s48, 0x100
	s_addc_u32 s49, s49, 0
	s_add_u32 s20, s20, 0x100
	s_addc_u32 s21, s21, 0
	s_cmp_ge_i32 s50, s34
	s_mov_b32 s22, s50
	s_cbranch_scc0 .LBB0_216
	v_readlane_b32 s54, v254, 25
	v_readlane_b32 s52, v254, 27
	v_readlane_b32 s55, v254, 26
	v_readlane_b32 s53, v254, 28
	s_mov_b32 s50, s94
	s_and_b64 vcc, exec, s[16:17]
	s_cbranch_vccnz .LBB0_221
	s_branch .LBB0_222

; #define PG8_STAGE(bufoff, gbase, voff) do { _Pragma("unroll") for (int _i = 0; _i < 2; ++_i) \
;         __builtin_amdgcn_global_load_lds((const unsigned*)((const char*)(gbase) + (voff)[_i]), (PG8_LAS unsigned*)(lds + (bufoff) + ldsw + _i * 8192), 16, 0, 0); } while (0)
; #define PG8_LDA(dst, b, h) do { _Pragma("unroll") for (int m = 0; m < 4; ++m) _Pragma("unroll") for (int k = 0; k < 2; ++k) dst[m][k] = *(const PG8_LAS bf16x8*)(lds + PG8_SA(b, h) + aoff + m * 2048 + k * 1024); } while (0)
; #define PG8_LDB(dst, b, h) do { _Pragma("unroll") for (int n = 0; n < 2; ++n) _Pragma("unroll") for (int k = 0; k < 2; ++k) dst[n][k] = *(const PG8_LAS bf16x8*)(lds + PG8_SB(b, h) + boff + n * 2048 + k * 1024); } while (0)
; #define PG8_MMA(ai, bj, At, Bt) do { __builtin_amdgcn_s_setprio(1); _Pragma("unroll") for (int m = 0; m < 4; ++m) _Pragma("unroll") for (int n = 0; n < 2; ++n) _Pragma("unroll") for (int k = 0; k < 2; ++k) \
;         acc[ai][bj][m][n] = __builtin_amdgcn_mfma_f32_16x16x32_bf16(Bt[n][k], At[m][k], acc[ai][bj][m][n], 0, 0, 0); __builtin_amdgcn_s_setprio(0); } while (0)
; #define PG8_WAIT_V(n) asm volatile("s_waitcnt vmcnt(" #n ")" ::: "memory")
; #define PG8_WAIT_L(n) asm volatile("s_waitcnt lgkmcnt(" #n ")" ::: "memory")
; #define PG8_BAR __builtin_amdgcn_s_barrier()
; #define PG8_SCHED __builtin_amdgcn_sched_barrier(0)
; template <class Epi, class Sched, bool ALIGN_EPI = false, bool SP2 = false, bool ACHUNK = false>
; __device__ __forceinline__ void gemm_phase(PG8_LAS unsigned char* lds, const Gemm g, const Sched& S, const Epi& E) {
;     ...
;             PG8_LDB(B0, 0, 0); PG8_LDB(B1, 0, 1); PG8_SCHED; PG8_LDA(At, 0, 0); PG8_STAGE(PG8_SA(1, 1), a1 + hstepA, voffA);
;             PG8_WAIT_V(8); PG8_WAIT_L(0); PG8_BAR; PG8_MMA(0, 0, At, B0); PG8_MMA(0, 1, At, B1); PG8_BAR; PG8_SCHED;
;             PG8_LDA(At, 0, 1); PG8_STAGE(PG8_SB(0, 0), b2, voffB); PG8_STAGE(PG8_SB(0, 1), b2 + hstepB, voffB); PG8_STAGE(PG8_SA(0, 0), a2, voffA);
;             PG8_WAIT_V(8); PG8_WAIT_L(0); PG8_BAR; PG8_MMA(1, 0, At, B0); PG8_MMA(1, 1, At, B1); PG8_BAR; PG8_SCHED;
.Lnl_mg:
	s_add_i32 s54, 0, 0x14000
	ds_read_b128 v[134:137], v2
	ds_read_b128 v[138:141], v2 offset:1024
	ds_read_b128 v[142:145], v2 offset:2048
	ds_read_b128 v[146:149], v2 offset:3072
	v_add_u32_e32 v2, s54, v235
	ds_read_b128 v[150:153], v2
	ds_read_b128 v[154:157], v2 offset:1024
	ds_read_b128 v[158:161], v2 offset:2048
	ds_read_b128 v[162:165], v2 offset:3072
	v_lshl_add_u64 v[4:5], v[210:211], 0, s[6:7]
	s_add_i32 m0, s17, 0xc000
	ds_read_b128 v[166:169], v237
	ds_read_b128 v[170:173], v237 offset:1024
	ds_read_b128 v[174:177], v237 offset:2048
	ds_read_b128 v[178:181], v237 offset:3072
	ds_read_b128 v[182:185], v237 offset:4096
	ds_read_b128 v[186:189], v237 offset:5120
	ds_read_b128 v[190:193], v237 offset:6144
	ds_read_b128 v[214:217], v237 offset:7168
	global_load_lds_dwordx4 v[4:5], off
	v_lshl_add_u64 v[4:5], v[212:213], 0, s[6:7]
	s_add_i32 m0, s17, 0xe000
	s_nop 0
	global_load_lds_dwordx4 v[4:5], off
	s_waitcnt vmcnt(8)
	s_waitcnt lgkmcnt(0)
	s_barrier
	s_setprio 1
	v_mfma_f32_16x16x32_bf16 v[126:129], v[134:137], v[166:169], v[126:129]
	v_mfma_f32_16x16x32_bf16 v[130:133], v[142:145], v[166:169], v[130:133]
	v_mfma_f32_16x16x32_bf16 v[114:117], v[134:137], v[174:177], v[114:117]
	v_mfma_f32_16x16x32_bf16 v[110:113], v[142:145], v[174:177], v[110:113]
	v_mfma_f32_16x16x32_bf16 v[98:101], v[134:137], v[182:185], v[98:101]
	v_mfma_f32_16x16x32_bf16 v[94:97], v[142:145], v[182:185], v[94:97]
	v_mfma_f32_16x16x32_bf16 v[82:85], v[134:137], v[190:193], v[82:85]
	v_mfma_f32_16x16x32_bf16 v[78:81], v[142:145], v[190:193], v[78:81]
	v_mfma_f32_16x16x32_bf16 v[126:129], v[138:141], v[170:173], v[126:129]
	v_mfma_f32_16x16x32_bf16 v[130:133], v[146:149], v[170:173], v[130:133]
	v_mfma_f32_16x16x32_bf16 v[114:117], v[138:141], v[178:181], v[114:117]
	v_mfma_f32_16x16x32_bf16 v[110:113], v[146:149], v[178:181], v[110:113]
	v_mfma_f32_16x16x32_bf16 v[98:101], v[138:141], v[186:189], v[98:101]
	v_mfma_f32_16x16x32_bf16 v[94:97], v[146:149], v[186:189], v[94:97]
	v_mfma_f32_16x16x32_bf16 v[82:85], v[138:141], v[214:217], v[82:85]
	v_mfma_f32_16x16x32_bf16 v[78:81], v[146:149], v[214:217], v[78:81]
	s_setprio 0
	s_setprio 1
	v_mfma_f32_16x16x32_bf16 v[122:125], v[150:153], v[166:169], v[122:125]
	v_mfma_f32_16x16x32_bf16 v[118:121], v[158:161], v[166:169], v[118:121]
	v_mfma_f32_16x16x32_bf16 v[106:109], v[150:153], v[174:177], v[106:109]
	v_mfma_f32_16x16x32_bf16 v[102:105], v[158:161], v[174:177], v[102:105]
	v_mfma_f32_16x16x32_bf16 v[90:93], v[150:153], v[182:185], v[90:93]
	v_mfma_f32_16x16x32_bf16 v[86:89], v[158:161], v[182:185], v[86:89]
	v_mfma_f32_16x16x32_bf16 v[74:77], v[150:153], v[190:193], v[74:77]
	v_mfma_f32_16x16x32_bf16 v[70:73], v[158:161], v[190:193], v[70:73]
	v_mfma_f32_16x16x32_bf16 v[122:125], v[154:157], v[170:173], v[122:125]
	v_mfma_f32_16x16x32_bf16 v[118:121], v[162:165], v[170:173], v[118:121]
	v_mfma_f32_16x16x32_bf16 v[106:109], v[154:157], v[178:181], v[106:109]
	v_mfma_f32_16x16x32_bf16 v[102:105], v[162:165], v[178:181], v[102:105]
	v_mfma_f32_16x16x32_bf16 v[90:93], v[154:157], v[186:189], v[90:93]
	v_mfma_f32_16x16x32_bf16 v[86:89], v[162:165], v[186:189], v[86:89]
	v_mfma_f32_16x16x32_bf16 v[74:77], v[154:157], v[214:217], v[74:77]
	v_mfma_f32_16x16x32_bf16 v[70:73], v[162:165], v[214:217], v[70:73]
	s_setprio 0
	s_barrier
	s_add_i32 s55, s55, s16
	s_mov_b32 m0, s55
	ds_read_b128 v[166:169], v237 offset:16384
	ds_read_b128 v[170:173], v237 offset:17408
	ds_read_b128 v[174:177], v237 offset:18432
	ds_read_b128 v[178:181], v237 offset:19456
	ds_read_b128 v[182:185], v237 offset:20480
	ds_read_b128 v[186:189], v237 offset:21504
	ds_read_b128 v[190:193], v237 offset:22528
	ds_read_b128 v[214:217], v237 offset:23552
	global_load_lds_dwordx4 v200, s[52:53]
	s_add_i32 m0, s55, 0x2000
	s_add_i32 s54, s54, s16
	global_load_lds_dwordx4 v204, s[52:53]
	s_add_u32 s52, s52, s2
	s_addc_u32 s53, s53, s3
	s_mov_b64 vcc, s[52:53]
	s_sub_u32 s98, s52, s2
	s_subb_u32 s99, s53, s3
	s_mov_b32 m0, s54
	s_nop 0
	global_load_lds_dwordx4 v200, s[52:53]
	s_add_i32 m0, s54, 0x2000
	s_nop 0
	global_load_lds_dwordx4 v204, s[52:53]
	s_mov_b32 m0, s17
	s_nop 0
	global_load_lds_dwordx4 v198, s[8:9]
	s_mov_b32 m0, s20
	s_nop 0
	global_load_lds_dwordx4 v202, s[8:9]
	s_waitcnt vmcnt(8)
	s_waitcnt lgkmcnt(0)
	s_barrier
	s_setprio 1
	v_mfma_f32_16x16x32_bf16 v[66:69], v[134:137], v[166:169], v[66:69]
	v_mfma_f32_16x16x32_bf16 v[62:65], v[142:145], v[166:169], v[62:65]
	v_mfma_f32_16x16x32_bf16 v[50:53], v[134:137], v[174:177], v[50:53]
	v_mfma_f32_16x16x32_bf16 v[46:49], v[142:145], v[174:177], v[46:49]
	v_mfma_f32_16x16x32_bf16 v[34:37], v[134:137], v[182:185], v[34:37]
	v_mfma_f32_16x16x32_bf16 v[30:33], v[142:145], v[182:185], v[30:33]
	v_mfma_f32_16x16x32_bf16 v[18:21], v[134:137], v[190:193], v[18:21]
	v_mfma_f32_16x16x32_bf16 v[14:17], v[142:145], v[190:193], v[14:17]
	v_mfma_f32_16x16x32_bf16 v[66:69], v[138:141], v[170:173], v[66:69]
	v_mfma_f32_16x16x32_bf16 v[62:65], v[146:149], v[170:173], v[62:65]
	v_mfma_f32_16x16x32_bf16 v[50:53], v[138:141], v[178:181], v[50:53]
	v_mfma_f32_16x16x32_bf16 v[46:49], v[146:149], v[178:181], v[46:49]
	v_mfma_f32_16x16x32_bf16 v[34:37], v[138:141], v[186:189], v[34:37]
	v_mfma_f32_16x16x32_bf16 v[30:33], v[146:149], v[186:189], v[30:33]
	v_mfma_f32_16x16x32_bf16 v[18:21], v[138:141], v[214:217], v[18:21]
	v_mfma_f32_16x16x32_bf16 v[14:17], v[146:149], v[214:217], v[14:17]
	s_setprio 0
	s_setprio 1
	v_mfma_f32_16x16x32_bf16 v[58:61], v[150:153], v[166:169], v[58:61]
	v_mfma_f32_16x16x32_bf16 v[54:57], v[158:161], v[166:169], v[54:57]
	v_mfma_f32_16x16x32_bf16 v[42:45], v[150:153], v[174:177], v[42:45]
	v_mfma_f32_16x16x32_bf16 v[38:41], v[158:161], v[174:177], v[38:41]
	v_mfma_f32_16x16x32_bf16 v[26:29], v[150:153], v[182:185], v[26:29]
	v_mfma_f32_16x16x32_bf16 v[22:25], v[158:161], v[182:185], v[22:25]
	v_mfma_f32_16x16x32_bf16 v[10:13], v[150:153], v[190:193], v[10:13]
	v_mfma_f32_16x16x32_bf16 v[4:7], v[158:161], v[190:193], v[6:9]
	v_mfma_f32_16x16x32_bf16 v[58:61], v[154:157], v[170:173], v[58:61]
	v_mfma_f32_16x16x32_bf16 v[54:57], v[162:165], v[170:173], v[54:57]
	v_mfma_f32_16x16x32_bf16 v[42:45], v[154:157], v[178:181], v[42:45]
	v_mfma_f32_16x16x32_bf16 v[38:41], v[162:165], v[178:181], v[38:41]
	v_mfma_f32_16x16x32_bf16 v[26:29], v[154:157], v[186:189], v[26:29]
	v_mfma_f32_16x16x32_bf16 v[22:25], v[162:165], v[186:189], v[22:25]
	v_mfma_f32_16x16x32_bf16 v[10:13], v[154:157], v[214:217], v[10:13]
	v_mfma_f32_16x16x32_bf16 v[4:7], v[162:165], v[214:217], v[4:7]
	s_setprio 0
	s_barrier
; #define PG8_STAGE(bufoff, gbase, voff) do { _Pragma("unroll") for (int _i = 0; _i < 2; ++_i) \
;         __builtin_amdgcn_global_load_lds((const unsigned*)((const char*)(gbase) + (voff)[_i]), (PG8_LAS unsigned*)(lds + (bufoff) + ldsw + _i * 8192), 16, 0, 0); } while (0)
; #define PG8_LDA(dst, b, h) do { _Pragma("unroll") for (int m = 0; m < 4; ++m) _Pragma("unroll") for (int k = 0; k < 2; ++k) dst[m][k] = *(const PG8_LAS bf16x8*)(lds + PG8_SA(b, h) + aoff + m * 2048 + k * 1024); } while (0)
; #define PG8_LDB(dst, b, h) do { _Pragma("unroll") for (int n = 0; n < 2; ++n) _Pragma("unroll") for (int k = 0; k < 2; ++k) dst[n][k] = *(const PG8_LAS bf16x8*)(lds + PG8_SB(b, h) + boff + n * 2048 + k * 1024); } while (0)
; #define PG8_MMA(ai, bj, At, Bt) do { __builtin_amdgcn_s_setprio(1); _Pragma("unroll") for (int m = 0; m < 4; ++m) _Pragma("unroll") for (int n = 0; n < 2; ++n) _Pragma("unroll") for (int k = 0; k < 2; ++k) \
;         acc[ai][bj][m][n] = __builtin_amdgcn_mfma_f32_16x16x32_bf16(Bt[n][k], At[m][k], acc[ai][bj][m][n], 0, 0, 0); __builtin_amdgcn_s_setprio(0); } while (0)
; #define PG8_WAIT_V(n) asm volatile("s_waitcnt vmcnt(" #n ")" ::: "memory")
; #define PG8_WAIT_L(n) asm volatile("s_waitcnt lgkmcnt(" #n ")" ::: "memory")
; #define PG8_BAR __builtin_amdgcn_s_barrier()
; #define PG8_SCHED __builtin_amdgcn_sched_barrier(0)
; template <class Epi, class Sched, bool ALIGN_EPI = false, bool SP2 = false, bool ACHUNK = false>
; __device__ __forceinline__ void gemm_phase(PG8_LAS unsigned char* lds, const Gemm g, const Sched& S, const Epi& E) {
;     ...
;             PG8_LDB(B0, 1, 0); PG8_LDB(B1, 1, 1); PG8_SCHED; PG8_LDA(At, 1, 0); PG8_STAGE(PG8_SA(0, 1), a2 + hstepA, voffA);
;             PG8_WAIT_V(8); PG8_WAIT_L(0); PG8_BAR; PG8_MMA(0, 0, At, B0); PG8_MMA(0, 1, At, B1); PG8_BAR; PG8_SCHED;
;             PG8_LDA(At, 1, 1); PG8_STAGE(PG8_SB(1, 0), b3, voffB); PG8_STAGE(PG8_SB(1, 1), b3 + hstepB, voffB); PG8_STAGE(PG8_SA(1, 0), a3, voffA);
;             PG8_WAIT_V(8); PG8_WAIT_L(0); PG8_BAR; PG8_MMA(1, 0, At, B0); PG8_MMA(1, 1, At, B1); PG8_BAR; PG8_SCHED;
	s_add_i32 s52, 0, 0x18000
	v_add_u32_e32 v2, s52, v235
	s_add_i32 s53, 0, 0x1c000
	ds_read_b128 v[134:137], v2
	ds_read_b128 v[138:141], v2 offset:1024
	ds_read_b128 v[142:145], v2 offset:2048
	ds_read_b128 v[146:149], v2 offset:3072
	v_add_u32_e32 v2, s53, v235
	ds_read_b128 v[150:153], v2
	ds_read_b128 v[154:157], v2 offset:1024
	ds_read_b128 v[158:161], v2 offset:2048
	ds_read_b128 v[162:165], v2 offset:3072
	s_add_u32 s8, s8, s2
	s_addc_u32 s9, s9, s3
	s_mov_b32 m0, s21
	ds_read_b128 v[166:169], v237 offset:32768
	ds_read_b128 v[170:173], v237 offset:33792
	ds_read_b128 v[174:177], v237 offset:34816
	ds_read_b128 v[178:181], v237 offset:35840
	ds_read_b128 v[182:185], v237 offset:36864
	ds_read_b128 v[186:189], v237 offset:37888
	ds_read_b128 v[190:193], v237 offset:38912
	ds_read_b128 v[214:217], v237 offset:39936
	global_load_lds_dwordx4 v198, s[8:9]
	s_mov_b32 m0, s22
	s_nop 0
	global_load_lds_dwordx4 v202, s[8:9]
	s_waitcnt vmcnt(8)
	s_waitcnt lgkmcnt(0)
	s_barrier
	s_setprio 1
	v_mfma_f32_16x16x32_bf16 v[126:129], v[134:137], v[166:169], v[126:129]
	v_mfma_f32_16x16x32_bf16 v[130:133], v[142:145], v[166:169], v[130:133]
	v_mfma_f32_16x16x32_bf16 v[114:117], v[134:137], v[174:177], v[114:117]
	v_mfma_f32_16x16x32_bf16 v[110:113], v[142:145], v[174:177], v[110:113]
	v_mfma_f32_16x16x32_bf16 v[98:101], v[134:137], v[182:185], v[98:101]
	v_mfma_f32_16x16x32_bf16 v[94:97], v[142:145], v[182:185], v[94:97]
	v_mfma_f32_16x16x32_bf16 v[82:85], v[134:137], v[190:193], v[82:85]
	v_mfma_f32_16x16x32_bf16 v[78:81], v[142:145], v[190:193], v[78:81]
	v_mfma_f32_16x16x32_bf16 v[126:129], v[138:141], v[170:173], v[126:129]
	v_mfma_f32_16x16x32_bf16 v[130:133], v[146:149], v[170:173], v[130:133]
	v_mfma_f32_16x16x32_bf16 v[114:117], v[138:141], v[178:181], v[114:117]
	v_mfma_f32_16x16x32_bf16 v[110:113], v[146:149], v[178:181], v[110:113]
	v_mfma_f32_16x16x32_bf16 v[98:101], v[138:141], v[186:189], v[98:101]
	v_mfma_f32_16x16x32_bf16 v[94:97], v[146:149], v[186:189], v[94:97]
	v_mfma_f32_16x16x32_bf16 v[82:85], v[138:141], v[214:217], v[82:85]
	v_mfma_f32_16x16x32_bf16 v[78:81], v[146:149], v[214:217], v[78:81]
	s_setprio 0
	s_setprio 1
	v_mfma_f32_16x16x32_bf16 v[122:125], v[150:153], v[166:169], v[122:125]
	v_mfma_f32_16x16x32_bf16 v[118:121], v[158:161], v[166:169], v[118:121]
	v_mfma_f32_16x16x32_bf16 v[106:109], v[150:153], v[174:177], v[106:109]
	v_mfma_f32_16x16x32_bf16 v[102:105], v[158:161], v[174:177], v[102:105]
	v_mfma_f32_16x16x32_bf16 v[90:93], v[150:153], v[182:185], v[90:93]
	v_mfma_f32_16x16x32_bf16 v[86:89], v[158:161], v[182:185], v[86:89]
	v_mfma_f32_16x16x32_bf16 v[74:77], v[150:153], v[190:193], v[74:77]
	v_mfma_f32_16x16x32_bf16 v[70:73], v[158:161], v[190:193], v[70:73]
	v_mfma_f32_16x16x32_bf16 v[122:125], v[154:157], v[170:173], v[122:125]
	v_mfma_f32_16x16x32_bf16 v[118:121], v[162:165], v[170:173], v[118:121]
	v_mfma_f32_16x16x32_bf16 v[106:109], v[154:157], v[178:181], v[106:109]
	v_mfma_f32_16x16x32_bf16 v[102:105], v[162:165], v[178:181], v[102:105]
	v_mfma_f32_16x16x32_bf16 v[90:93], v[154:157], v[186:189], v[90:93]
	v_mfma_f32_16x16x32_bf16 v[86:89], v[162:165], v[186:189], v[86:89]
	v_mfma_f32_16x16x32_bf16 v[74:77], v[154:157], v[214:217], v[74:77]
	v_mfma_f32_16x16x32_bf16 v[70:73], v[162:165], v[214:217], v[70:73]
	s_setprio 0
	s_barrier
	s_add_u32 vcc_lo, vcc_lo, s10
	s_addc_u32 vcc_hi, vcc_hi, s11
	s_add_u32 s98, s98, s10
	s_addc_u32 s99, s99, s11
	s_sub_u32 s8, s8, s2
	s_subb_u32 s9, s9, s3
	s_add_u32 s8, s8, s10
	s_addc_u32 s9, s9, s11
	s_add_i32 m0, s52, s16
	ds_read_b128 v[166:169], v237 offset:49152
	ds_read_b128 v[170:173], v237 offset:50176
	ds_read_b128 v[174:177], v237 offset:51200
	ds_read_b128 v[178:181], v237 offset:52224
	ds_read_b128 v[182:185], v237 offset:53248
	ds_read_b128 v[186:189], v237 offset:54272
	ds_read_b128 v[190:193], v237 offset:55296
	ds_read_b128 v[214:217], v237 offset:56320
	global_load_lds_dwordx4 v200, s[98:99]
	s_add_i32 m0, m0, 0x2000
	s_nop 0
	global_load_lds_dwordx4 v204, s[98:99]
	s_add_i32 m0, s53, s16
	s_nop 0
	global_load_lds_dwordx4 v200, vcc
	s_add_i32 m0, m0, 0x2000
	s_nop 0
	global_load_lds_dwordx4 v204, vcc
	s_mov_b32 m0, s26
	s_nop 0
	global_load_lds_dwordx4 v198, s[8:9]
	s_mov_b32 m0, s27
	s_nop 0
	global_load_lds_dwordx4 v202, s[8:9]
	s_waitcnt vmcnt(8)
	s_waitcnt lgkmcnt(0)
	s_barrier
	s_setprio 1
	v_mfma_f32_16x16x32_bf16 v[66:69], v[134:137], v[166:169], v[66:69]
	v_mfma_f32_16x16x32_bf16 v[62:65], v[142:145], v[166:169], v[62:65]
	v_mfma_f32_16x16x32_bf16 v[50:53], v[134:137], v[174:177], v[50:53]
	v_mfma_f32_16x16x32_bf16 v[46:49], v[142:145], v[174:177], v[46:49]
	v_mfma_f32_16x16x32_bf16 v[34:37], v[134:137], v[182:185], v[34:37]
	v_mfma_f32_16x16x32_bf16 v[30:33], v[142:145], v[182:185], v[30:33]
	v_mfma_f32_16x16x32_bf16 v[18:21], v[134:137], v[190:193], v[18:21]
	v_mfma_f32_16x16x32_bf16 v[14:17], v[142:145], v[190:193], v[14:17]
	v_mfma_f32_16x16x32_bf16 v[66:69], v[138:141], v[170:173], v[66:69]
	v_mfma_f32_16x16x32_bf16 v[62:65], v[146:149], v[170:173], v[62:65]
	v_mfma_f32_16x16x32_bf16 v[50:53], v[138:141], v[178:181], v[50:53]
	v_mfma_f32_16x16x32_bf16 v[46:49], v[146:149], v[178:181], v[46:49]
	v_mfma_f32_16x16x32_bf16 v[34:37], v[138:141], v[186:189], v[34:37]
	v_mfma_f32_16x16x32_bf16 v[30:33], v[146:149], v[186:189], v[30:33]
	v_mfma_f32_16x16x32_bf16 v[18:21], v[138:141], v[214:217], v[18:21]
	v_mfma_f32_16x16x32_bf16 v[14:17], v[146:149], v[214:217], v[14:17]
	s_setprio 0
	s_setprio 1
	v_mfma_f32_16x16x32_bf16 v[58:61], v[150:153], v[166:169], v[58:61]
	v_mfma_f32_16x16x32_bf16 v[54:57], v[158:161], v[166:169], v[54:57]
	v_mfma_f32_16x16x32_bf16 v[42:45], v[150:153], v[174:177], v[42:45]
	v_mfma_f32_16x16x32_bf16 v[38:41], v[158:161], v[174:177], v[38:41]
	v_mfma_f32_16x16x32_bf16 v[26:29], v[150:153], v[182:185], v[26:29]
	v_mfma_f32_16x16x32_bf16 v[22:25], v[158:161], v[182:185], v[22:25]
	v_mfma_f32_16x16x32_bf16 v[8:11], v[150:153], v[190:193], v[10:13]
	v_mfma_f32_16x16x32_bf16 v[4:7], v[158:161], v[190:193], v[4:7]
	v_mfma_f32_16x16x32_bf16 v[58:61], v[154:157], v[170:173], v[58:61]
	v_mfma_f32_16x16x32_bf16 v[54:57], v[162:165], v[170:173], v[54:57]
	v_mfma_f32_16x16x32_bf16 v[42:45], v[154:157], v[178:181], v[42:45]
	v_mfma_f32_16x16x32_bf16 v[38:41], v[162:165], v[178:181], v[38:41]
	v_mfma_f32_16x16x32_bf16 v[26:29], v[154:157], v[186:189], v[26:29]
	v_mfma_f32_16x16x32_bf16 v[22:25], v[162:165], v[186:189], v[22:25]
	v_mfma_f32_16x16x32_bf16 v[10:13], v[154:157], v[214:217], v[8:11]
	v_mfma_f32_16x16x32_bf16 v[6:9], v[162:165], v[214:217], v[4:7]
	s_setprio 0
	s_barrier
	s_add_u32 s6, s6, 0x100
	s_addc_u32 s7, s7, 0
	s_cmp_ge_i32 s51, s23
	s_cbranch_scc0 .LBB0_266
	v_readlane_b32 s54, v254, 25
	v_readlane_b32 s52, v254, 27
	v_readlane_b32 s55, v254, 26
	v_readlane_b32 s53, v254, 28
	v_readlane_b32 s47, v255, 0
	s_mov_b32 s50, s94

; #define PG8_STAGE(bufoff, gbase, voff) do { _Pragma("unroll") for (int _i = 0; _i < 2; ++_i) \
;         __builtin_amdgcn_global_load_lds((const unsigned*)((const char*)(gbase) + (voff)[_i]), (PG8_LAS unsigned*)(lds + (bufoff) + ldsw + _i * 8192), 16, 0, 0); } while (0)
; #define PG8_LDA(dst, b, h) do { _Pragma("unroll") for (int m = 0; m < 4; ++m) _Pragma("unroll") for (int k = 0; k < 2; ++k) dst[m][k] = *(const PG8_LAS bf16x8*)(lds + PG8_SA(b, h) + aoff + m * 2048 + k * 1024); } while (0)
; #define PG8_LDB(dst, b, h) do { _Pragma("unroll") for (int n = 0; n < 2; ++n) _Pragma("unroll") for (int k = 0; k < 2; ++k) dst[n][k] = *(const PG8_LAS bf16x8*)(lds + PG8_SB(b, h) + boff + n * 2048 + k * 1024); } while (0)
; #define PG8_MMA(ai, bj, At, Bt) do { __builtin_amdgcn_s_setprio(1); _Pragma("unroll") for (int m = 0; m < 4; ++m) _Pragma("unroll") for (int n = 0; n < 2; ++n) _Pragma("unroll") for (int k = 0; k < 2; ++k) \
;         acc[ai][bj][m][n] = __builtin_amdgcn_mfma_f32_16x16x32_bf16(Bt[n][k], At[m][k], acc[ai][bj][m][n], 0, 0, 0); __builtin_amdgcn_s_setprio(0); } while (0)
; #define PG8_WAIT_V(n) asm volatile("s_waitcnt vmcnt(" #n ")" ::: "memory")
; #define PG8_WAIT_L(n) asm volatile("s_waitcnt lgkmcnt(" #n ")" ::: "memory")
; #define PG8_BAR __builtin_amdgcn_s_barrier()
; template <class Epi, class Sched, bool ALIGN_EPI = false, bool SP2 = false, bool ACHUNK = false>
; __device__ __forceinline__ void gemm_phase(PG8_LAS unsigned char* lds, const Gemm g, const Sched& S, const Epi& E) {
;     ...
;             const char* a1 = cA + (size_t)(t + 1) * kstep;
;             const char* a2 = last ? nA : cA + (size_t)(t + 2) * kstep; const char* b2 = last ? nB : cB + (size_t)(t + 2) * kstep;
;             const char* a3 = a2 + kstep; const char* b3 = b2 + kstep;
;             if (last && has_next) S.a_ready(nxt);
;             if constexpr (SP2) {
;             PG8_LDB(B0, 0, 0); PG8_LDB(B1, 0, 1); PG8_SCHED; PG8_LDA(At, 0, 0); PG8_STAGE(PG8_SA(1, 1), a1 + hstepA, voffA);
;             PG8_WAIT_V(8); PG8_WAIT_L(0); PG8_BAR; PG8_MMA(0, 0, At, B0); PG8_MMA(0, 1, At, B1); PG8_BAR; PG8_SCHED;
;             PG8_LDA(At, 0, 1); PG8_STAGE(PG8_SB(0, 0), b2, voffB); PG8_STAGE(PG8_SB(0, 1), b2 + hstepB, voffB); PG8_STAGE(PG8_SA(0, 0), a2, voffA);
;             PG8_WAIT_V(8); PG8_WAIT_L(0); PG8_BAR; PG8_MMA(1, 0, At, B0); PG8_MMA(1, 1, At, B1); PG8_BAR; PG8_SCHED;
.LBB0_353:
	s_add_i32 s42, s20, 2
	s_add_u32 s43, s18, 0x80
	s_addc_u32 s21, s19, 0
	s_add_i32 s46, 0, 0x10000
	s_cmp_eq_u32 s33, s20
	s_cselect_b32 s21, s13, s21
	s_cselect_b32 s20, s12, s43
	v_add_u32_e32 v153, s46, v143
	s_cselect_b32 s45, s17, s41
	s_cselect_b32 s44, s16, s40
	s_add_i32 s43, 0, 0x14000
	ds_read_b128 v[154:157], v153
	ds_read_b128 v[158:161], v153 offset:1024
	ds_read_b128 v[162:165], v153 offset:2048
	ds_read_b128 v[166:169], v153 offset:3072
	v_add_u32_e32 v153, s43, v143
	ds_read_b128 v[170:173], v153
	ds_read_b128 v[174:177], v153 offset:1024
	ds_read_b128 v[178:181], v153 offset:2048
	ds_read_b128 v[182:185], v153 offset:3072
	s_add_i32 m0, s25, 0xc000
	ds_read_b128 v[186:189], v152
	ds_read_b128 v[190:193], v152 offset:1024
	ds_read_b128 v[198:201], v152 offset:2048
	ds_read_b128 v[202:205], v152 offset:3072
	ds_read_b128 v[206:209], v152 offset:4096
	ds_read_b128 v[210:213], v152 offset:5120
	ds_read_b128 v[214:217], v152 offset:6144
	ds_read_b128 v[218:221], v152 offset:7168
	global_load_lds_dwordx4 v138, s[18:19]
	s_add_i32 m0, s25, 0xe000
	s_nop 0
	global_load_lds_dwordx4 v140, s[18:19]
	s_waitcnt vmcnt(8)
	s_waitcnt lgkmcnt(0)
	s_barrier
	s_setprio 1
	v_mfma_f32_16x16x32_bf16 v[124:127], v[154:157], v[186:189], v[124:127]
	v_mfma_f32_16x16x32_bf16 v[128:131], v[162:165], v[186:189], v[128:131]
	v_mfma_f32_16x16x32_bf16 v[112:115], v[154:157], v[198:201], v[112:115]
	v_mfma_f32_16x16x32_bf16 v[108:111], v[162:165], v[198:201], v[108:111]
	v_mfma_f32_16x16x32_bf16 v[96:99], v[154:157], v[206:209], v[96:99]
	v_mfma_f32_16x16x32_bf16 v[92:95], v[162:165], v[206:209], v[92:95]
	v_mfma_f32_16x16x32_bf16 v[80:83], v[154:157], v[214:217], v[80:83]
	v_mfma_f32_16x16x32_bf16 v[76:79], v[162:165], v[214:217], v[76:79]
	v_mfma_f32_16x16x32_bf16 v[124:127], v[158:161], v[190:193], v[124:127]
	v_mfma_f32_16x16x32_bf16 v[128:131], v[166:169], v[190:193], v[128:131]
	v_mfma_f32_16x16x32_bf16 v[112:115], v[158:161], v[202:205], v[112:115]
	v_mfma_f32_16x16x32_bf16 v[108:111], v[166:169], v[202:205], v[108:111]
	v_mfma_f32_16x16x32_bf16 v[96:99], v[158:161], v[210:213], v[96:99]
	v_mfma_f32_16x16x32_bf16 v[92:95], v[166:169], v[210:213], v[92:95]
	v_mfma_f32_16x16x32_bf16 v[80:83], v[158:161], v[218:221], v[80:83]
	v_mfma_f32_16x16x32_bf16 v[76:79], v[166:169], v[218:221], v[76:79]
	s_setprio 0
	s_setprio 1
	v_mfma_f32_16x16x32_bf16 v[120:123], v[170:173], v[186:189], v[120:123]
	v_mfma_f32_16x16x32_bf16 v[116:119], v[178:181], v[186:189], v[116:119]
	v_mfma_f32_16x16x32_bf16 v[104:107], v[170:173], v[198:201], v[104:107]
	v_mfma_f32_16x16x32_bf16 v[100:103], v[178:181], v[198:201], v[100:103]
	v_mfma_f32_16x16x32_bf16 v[88:91], v[170:173], v[206:209], v[88:91]
	v_mfma_f32_16x16x32_bf16 v[84:87], v[178:181], v[206:209], v[84:87]
	v_mfma_f32_16x16x32_bf16 v[72:75], v[170:173], v[214:217], v[72:75]
	v_mfma_f32_16x16x32_bf16 v[68:71], v[178:181], v[214:217], v[68:71]
	v_mfma_f32_16x16x32_bf16 v[120:123], v[174:177], v[190:193], v[120:123]
	v_mfma_f32_16x16x32_bf16 v[116:119], v[182:185], v[190:193], v[116:119]
	v_mfma_f32_16x16x32_bf16 v[104:107], v[174:177], v[202:205], v[104:107]
	v_mfma_f32_16x16x32_bf16 v[100:103], v[182:185], v[202:205], v[100:103]
	v_mfma_f32_16x16x32_bf16 v[88:91], v[174:177], v[210:213], v[88:91]
	v_mfma_f32_16x16x32_bf16 v[84:87], v[182:185], v[210:213], v[84:87]
	v_mfma_f32_16x16x32_bf16 v[72:75], v[174:177], v[218:221], v[72:75]
	v_mfma_f32_16x16x32_bf16 v[68:71], v[182:185], v[218:221], v[68:71]
	s_setprio 0
	s_barrier
	s_add_i32 s46, s46, s24
	s_mov_b32 m0, s46
	ds_read_b128 v[186:189], v152 offset:16384
	ds_read_b128 v[190:193], v152 offset:17408
	ds_read_b128 v[198:201], v152 offset:18432
	ds_read_b128 v[202:205], v152 offset:19456
	ds_read_b128 v[206:209], v152 offset:20480
	ds_read_b128 v[210:213], v152 offset:21504
	ds_read_b128 v[214:217], v152 offset:22528
	ds_read_b128 v[218:221], v152 offset:23552
	global_load_lds_dwordx4 v2, s[44:45]
	s_add_i32 m0, s46, 0x2000
	s_add_i32 s43, s43, s24
	global_load_lds_dwordx4 v136, s[44:45]
	s_add_u32 s44, s44, s0
	s_addc_u32 s45, s45, s1
	s_mov_b64 vcc, s[44:45]
	s_sub_u32 s98, s44, s0
	s_subb_u32 s99, s45, s1
	s_mov_b32 m0, s43
	s_nop 0
	global_load_lds_dwordx4 v2, s[44:45]
	s_add_i32 m0, s43, 0x2000
	s_nop 0
	global_load_lds_dwordx4 v136, s[44:45]
	s_mov_b32 m0, s25
	s_nop 0
	global_load_lds_dwordx4 v132, s[20:21]
	s_mov_b32 m0, s26
	s_nop 0
	global_load_lds_dwordx4 v134, s[20:21]
	s_waitcnt vmcnt(8)
	s_waitcnt lgkmcnt(0)
	s_barrier
	s_setprio 1
	v_mfma_f32_16x16x32_bf16 v[64:67], v[154:157], v[186:189], v[64:67]
	v_mfma_f32_16x16x32_bf16 v[60:63], v[162:165], v[186:189], v[60:63]
	v_mfma_f32_16x16x32_bf16 v[48:51], v[154:157], v[198:201], v[48:51]
	v_mfma_f32_16x16x32_bf16 v[44:47], v[162:165], v[198:201], v[44:47]
	v_mfma_f32_16x16x32_bf16 v[32:35], v[154:157], v[206:209], v[32:35]
	v_mfma_f32_16x16x32_bf16 v[28:31], v[162:165], v[206:209], v[28:31]
	v_mfma_f32_16x16x32_bf16 v[16:19], v[154:157], v[214:217], v[16:19]
	v_mfma_f32_16x16x32_bf16 v[12:15], v[162:165], v[214:217], v[12:15]
	v_mfma_f32_16x16x32_bf16 v[64:67], v[158:161], v[190:193], v[64:67]
	v_mfma_f32_16x16x32_bf16 v[60:63], v[166:169], v[190:193], v[60:63]
	v_mfma_f32_16x16x32_bf16 v[48:51], v[158:161], v[202:205], v[48:51]
	v_mfma_f32_16x16x32_bf16 v[44:47], v[166:169], v[202:205], v[44:47]
	v_mfma_f32_16x16x32_bf16 v[32:35], v[158:161], v[210:213], v[32:35]
	v_mfma_f32_16x16x32_bf16 v[28:31], v[166:169], v[210:213], v[28:31]
	v_mfma_f32_16x16x32_bf16 v[16:19], v[158:161], v[218:221], v[16:19]
	v_mfma_f32_16x16x32_bf16 v[12:15], v[166:169], v[218:221], v[12:15]
	s_setprio 0
	s_setprio 1
	v_mfma_f32_16x16x32_bf16 v[56:59], v[170:173], v[186:189], v[56:59]
	v_mfma_f32_16x16x32_bf16 v[52:55], v[178:181], v[186:189], v[52:55]
	v_mfma_f32_16x16x32_bf16 v[40:43], v[170:173], v[198:201], v[40:43]
	v_mfma_f32_16x16x32_bf16 v[36:39], v[178:181], v[198:201], v[36:39]
	v_mfma_f32_16x16x32_bf16 v[24:27], v[170:173], v[206:209], v[24:27]
	v_mfma_f32_16x16x32_bf16 v[20:23], v[178:181], v[206:209], v[20:23]
	v_mfma_f32_16x16x32_bf16 v[8:11], v[170:173], v[214:217], v[8:11]
	v_mfma_f32_16x16x32_bf16 v[4:7], v[178:181], v[214:217], v[4:7]
	v_mfma_f32_16x16x32_bf16 v[56:59], v[174:177], v[190:193], v[56:59]
	v_mfma_f32_16x16x32_bf16 v[52:55], v[182:185], v[190:193], v[52:55]
	v_mfma_f32_16x16x32_bf16 v[40:43], v[174:177], v[202:205], v[40:43]
	v_mfma_f32_16x16x32_bf16 v[36:39], v[182:185], v[202:205], v[36:39]
	v_mfma_f32_16x16x32_bf16 v[24:27], v[174:177], v[210:213], v[24:27]
	v_mfma_f32_16x16x32_bf16 v[20:23], v[182:185], v[210:213], v[20:23]
	v_mfma_f32_16x16x32_bf16 v[8:11], v[174:177], v[218:221], v[8:11]
	v_mfma_f32_16x16x32_bf16 v[4:7], v[182:185], v[218:221], v[4:7]
	s_setprio 0
	s_barrier
; #define PG8_STAGE(bufoff, gbase, voff) do { _Pragma("unroll") for (int _i = 0; _i < 2; ++_i) \
;         __builtin_amdgcn_global_load_lds((const unsigned*)((const char*)(gbase) + (voff)[_i]), (PG8_LAS unsigned*)(lds + (bufoff) + ldsw + _i * 8192), 16, 0, 0); } while (0)
; #define PG8_LDA(dst, b, h) do { _Pragma("unroll") for (int m = 0; m < 4; ++m) _Pragma("unroll") for (int k = 0; k < 2; ++k) dst[m][k] = *(const PG8_LAS bf16x8*)(lds + PG8_SA(b, h) + aoff + m * 2048 + k * 1024); } while (0)
; #define PG8_LDB(dst, b, h) do { _Pragma("unroll") for (int n = 0; n < 2; ++n) _Pragma("unroll") for (int k = 0; k < 2; ++k) dst[n][k] = *(const PG8_LAS bf16x8*)(lds + PG8_SB(b, h) + boff + n * 2048 + k * 1024); } while (0)
; #define PG8_MMA(ai, bj, At, Bt) do { __builtin_amdgcn_s_setprio(1); _Pragma("unroll") for (int m = 0; m < 4; ++m) _Pragma("unroll") for (int n = 0; n < 2; ++n) _Pragma("unroll") for (int k = 0; k < 2; ++k) \
;         acc[ai][bj][m][n] = __builtin_amdgcn_mfma_f32_16x16x32_bf16(Bt[n][k], At[m][k], acc[ai][bj][m][n], 0, 0, 0); __builtin_amdgcn_s_setprio(0); } while (0)
; #define PG8_WAIT_V(n) asm volatile("s_waitcnt vmcnt(" #n ")" ::: "memory")
; #define PG8_WAIT_L(n) asm volatile("s_waitcnt lgkmcnt(" #n ")" ::: "memory")
; #define PG8_BAR __builtin_amdgcn_s_barrier()
; #define PG8_SCHED __builtin_amdgcn_sched_barrier(0)
; template <class Epi, class Sched, bool ALIGN_EPI = false, bool SP2 = false, bool ACHUNK = false>
; __device__ __forceinline__ void gemm_phase(PG8_LAS unsigned char* lds, const Gemm g, const Sched& S, const Epi& E) {
;     ...
;             PG8_LDB(B0, 1, 0); PG8_LDB(B1, 1, 1); PG8_SCHED; PG8_LDA(At, 1, 0); PG8_STAGE(PG8_SA(0, 1), a2 + hstepA, voffA);
;             PG8_WAIT_V(8); PG8_WAIT_L(0); PG8_BAR; PG8_MMA(0, 0, At, B0); PG8_MMA(0, 1, At, B1); PG8_BAR; PG8_SCHED;
;             PG8_LDA(At, 1, 1); PG8_STAGE(PG8_SB(1, 0), b3, voffB); PG8_STAGE(PG8_SB(1, 1), b3 + hstepB, voffB); PG8_STAGE(PG8_SA(1, 0), a3, voffA);
;             PG8_WAIT_V(8); PG8_WAIT_L(0); PG8_BAR; PG8_MMA(1, 0, At, B0); PG8_MMA(1, 1, At, B1); PG8_BAR; PG8_SCHED;
	s_add_i32 s43, 0, 0x18000
	v_add_u32_e32 v153, s43, v143
	s_add_i32 s44, 0, 0x1c000
	ds_read_b128 v[154:157], v153
	ds_read_b128 v[158:161], v153 offset:1024
	ds_read_b128 v[162:165], v153 offset:2048
	ds_read_b128 v[166:169], v153 offset:3072
	v_add_u32_e32 v153, s44, v143
	ds_read_b128 v[170:173], v153
	ds_read_b128 v[174:177], v153 offset:1024
	ds_read_b128 v[178:181], v153 offset:2048
	ds_read_b128 v[182:185], v153 offset:3072
	s_add_u32 s20, s20, s0
	s_addc_u32 s21, s21, s1
	s_mov_b32 m0, s27
	ds_read_b128 v[186:189], v152 offset:32768
	ds_read_b128 v[190:193], v152 offset:33792
	ds_read_b128 v[198:201], v152 offset:34816
	ds_read_b128 v[202:205], v152 offset:35840
	ds_read_b128 v[206:209], v152 offset:36864
	ds_read_b128 v[210:213], v152 offset:37888
	ds_read_b128 v[214:217], v152 offset:38912
	ds_read_b128 v[218:221], v152 offset:39936
	global_load_lds_dwordx4 v132, s[20:21]
	s_mov_b32 m0, s28
	s_nop 0
	global_load_lds_dwordx4 v134, s[20:21]
	s_waitcnt vmcnt(8)
	s_waitcnt lgkmcnt(0)
	s_barrier
	s_setprio 1
	v_mfma_f32_16x16x32_bf16 v[124:127], v[154:157], v[186:189], v[124:127]
	v_mfma_f32_16x16x32_bf16 v[128:131], v[162:165], v[186:189], v[128:131]
	v_mfma_f32_16x16x32_bf16 v[112:115], v[154:157], v[198:201], v[112:115]
	v_mfma_f32_16x16x32_bf16 v[108:111], v[162:165], v[198:201], v[108:111]
	v_mfma_f32_16x16x32_bf16 v[96:99], v[154:157], v[206:209], v[96:99]
	v_mfma_f32_16x16x32_bf16 v[92:95], v[162:165], v[206:209], v[92:95]
	v_mfma_f32_16x16x32_bf16 v[80:83], v[154:157], v[214:217], v[80:83]
	v_mfma_f32_16x16x32_bf16 v[76:79], v[162:165], v[214:217], v[76:79]
	v_mfma_f32_16x16x32_bf16 v[124:127], v[158:161], v[190:193], v[124:127]
	v_mfma_f32_16x16x32_bf16 v[128:131], v[166:169], v[190:193], v[128:131]
	v_mfma_f32_16x16x32_bf16 v[112:115], v[158:161], v[202:205], v[112:115]
	v_mfma_f32_16x16x32_bf16 v[108:111], v[166:169], v[202:205], v[108:111]
	v_mfma_f32_16x16x32_bf16 v[96:99], v[158:161], v[210:213], v[96:99]
	v_mfma_f32_16x16x32_bf16 v[92:95], v[166:169], v[210:213], v[92:95]
	v_mfma_f32_16x16x32_bf16 v[80:83], v[158:161], v[218:221], v[80:83]
	v_mfma_f32_16x16x32_bf16 v[76:79], v[166:169], v[218:221], v[76:79]
	s_setprio 0
	s_setprio 1
	v_mfma_f32_16x16x32_bf16 v[120:123], v[170:173], v[186:189], v[120:123]
	v_mfma_f32_16x16x32_bf16 v[116:119], v[178:181], v[186:189], v[116:119]
	v_mfma_f32_16x16x32_bf16 v[104:107], v[170:173], v[198:201], v[104:107]
	v_mfma_f32_16x16x32_bf16 v[100:103], v[178:181], v[198:201], v[100:103]
	v_mfma_f32_16x16x32_bf16 v[88:91], v[170:173], v[206:209], v[88:91]
	v_mfma_f32_16x16x32_bf16 v[84:87], v[178:181], v[206:209], v[84:87]
	v_mfma_f32_16x16x32_bf16 v[72:75], v[170:173], v[214:217], v[72:75]
	v_mfma_f32_16x16x32_bf16 v[68:71], v[178:181], v[214:217], v[68:71]
	v_mfma_f32_16x16x32_bf16 v[120:123], v[174:177], v[190:193], v[120:123]
	v_mfma_f32_16x16x32_bf16 v[116:119], v[182:185], v[190:193], v[116:119]
	v_mfma_f32_16x16x32_bf16 v[104:107], v[174:177], v[202:205], v[104:107]
	v_mfma_f32_16x16x32_bf16 v[100:103], v[182:185], v[202:205], v[100:103]
	v_mfma_f32_16x16x32_bf16 v[88:91], v[174:177], v[210:213], v[88:91]
	v_mfma_f32_16x16x32_bf16 v[84:87], v[182:185], v[210:213], v[84:87]
	v_mfma_f32_16x16x32_bf16 v[72:75], v[174:177], v[218:221], v[72:75]
	v_mfma_f32_16x16x32_bf16 v[68:71], v[182:185], v[218:221], v[68:71]
	s_setprio 0
	s_barrier
	s_add_u32 vcc_lo, vcc_lo, s10
	s_addc_u32 vcc_hi, vcc_hi, s11
	s_add_u32 s98, s98, s10
	s_addc_u32 s99, s99, s11
	s_sub_u32 s20, s20, s0
	s_subb_u32 s21, s21, s1
	s_add_u32 s20, s20, s10
	s_addc_u32 s21, s21, s11
	s_add_i32 m0, s43, s24
	ds_read_b128 v[186:189], v152 offset:49152
	ds_read_b128 v[190:193], v152 offset:50176
	ds_read_b128 v[198:201], v152 offset:51200
	ds_read_b128 v[202:205], v152 offset:52224
	ds_read_b128 v[206:209], v152 offset:53248
	ds_read_b128 v[210:213], v152 offset:54272
	ds_read_b128 v[214:217], v152 offset:55296
	ds_read_b128 v[218:221], v152 offset:56320
	global_load_lds_dwordx4 v2, s[98:99]
	s_add_i32 m0, m0, 0x2000
	s_nop 0
	global_load_lds_dwordx4 v136, s[98:99]
	s_add_i32 m0, s44, s24
	s_nop 0
	global_load_lds_dwordx4 v2, vcc
	s_add_i32 m0, m0, 0x2000
	s_nop 0
	global_load_lds_dwordx4 v136, vcc
	s_mov_b32 m0, s29
	s_nop 0
	global_load_lds_dwordx4 v132, s[20:21]
	s_mov_b32 m0, s30
	s_nop 0
	global_load_lds_dwordx4 v134, s[20:21]
	s_waitcnt vmcnt(8)
	s_waitcnt lgkmcnt(0)
	s_barrier
	s_setprio 1
	v_mfma_f32_16x16x32_bf16 v[64:67], v[154:157], v[186:189], v[64:67]
	v_mfma_f32_16x16x32_bf16 v[60:63], v[162:165], v[186:189], v[60:63]
	v_mfma_f32_16x16x32_bf16 v[48:51], v[154:157], v[198:201], v[48:51]
	v_mfma_f32_16x16x32_bf16 v[44:47], v[162:165], v[198:201], v[44:47]
	v_mfma_f32_16x16x32_bf16 v[32:35], v[154:157], v[206:209], v[32:35]
	v_mfma_f32_16x16x32_bf16 v[28:31], v[162:165], v[206:209], v[28:31]
	v_mfma_f32_16x16x32_bf16 v[16:19], v[154:157], v[214:217], v[16:19]
	v_mfma_f32_16x16x32_bf16 v[12:15], v[162:165], v[214:217], v[12:15]
	v_mfma_f32_16x16x32_bf16 v[64:67], v[158:161], v[190:193], v[64:67]
	v_mfma_f32_16x16x32_bf16 v[60:63], v[166:169], v[190:193], v[60:63]
	v_mfma_f32_16x16x32_bf16 v[48:51], v[158:161], v[202:205], v[48:51]
	v_mfma_f32_16x16x32_bf16 v[44:47], v[166:169], v[202:205], v[44:47]
	v_mfma_f32_16x16x32_bf16 v[32:35], v[158:161], v[210:213], v[32:35]
	v_mfma_f32_16x16x32_bf16 v[28:31], v[166:169], v[210:213], v[28:31]
	v_mfma_f32_16x16x32_bf16 v[16:19], v[158:161], v[218:221], v[16:19]
	v_mfma_f32_16x16x32_bf16 v[12:15], v[166:169], v[218:221], v[12:15]
	s_setprio 0
	s_setprio 1
	v_mfma_f32_16x16x32_bf16 v[56:59], v[170:173], v[186:189], v[56:59]
	v_mfma_f32_16x16x32_bf16 v[52:55], v[178:181], v[186:189], v[52:55]
	v_mfma_f32_16x16x32_bf16 v[40:43], v[170:173], v[198:201], v[40:43]
	v_mfma_f32_16x16x32_bf16 v[36:39], v[178:181], v[198:201], v[36:39]
	v_mfma_f32_16x16x32_bf16 v[24:27], v[170:173], v[206:209], v[24:27]
	v_mfma_f32_16x16x32_bf16 v[20:23], v[178:181], v[206:209], v[20:23]
	v_mfma_f32_16x16x32_bf16 v[8:11], v[170:173], v[214:217], v[8:11]
	v_mfma_f32_16x16x32_bf16 v[4:7], v[178:181], v[214:217], v[4:7]
	v_mfma_f32_16x16x32_bf16 v[56:59], v[174:177], v[190:193], v[56:59]
	v_mfma_f32_16x16x32_bf16 v[52:55], v[182:185], v[190:193], v[52:55]
	v_mfma_f32_16x16x32_bf16 v[40:43], v[174:177], v[202:205], v[40:43]
	v_mfma_f32_16x16x32_bf16 v[36:39], v[182:185], v[202:205], v[36:39]
	v_mfma_f32_16x16x32_bf16 v[24:27], v[174:177], v[210:213], v[24:27]
	v_mfma_f32_16x16x32_bf16 v[20:23], v[182:185], v[210:213], v[20:23]
	v_mfma_f32_16x16x32_bf16 v[8:11], v[174:177], v[218:221], v[8:11]
	v_mfma_f32_16x16x32_bf16 v[4:7], v[182:185], v[218:221], v[4:7]
	s_setprio 0
	s_barrier
	s_add_u32 s40, s40, 0x100
	s_addc_u32 s41, s41, 0
	s_add_u32 s18, s18, 0x100
	s_addc_u32 s19, s19, 0
	s_cmp_ge_i32 s42, s31
	s_mov_b32 s20, s42
	s_cbranch_scc0 .LBB0_353
	s_branch .LBB0_342

; #define PG8_STAGE(bufoff, gbase, voff) do { _Pragma("unroll") for (int _i = 0; _i < 2; ++_i) \
;         __builtin_amdgcn_global_load_lds((const unsigned*)((const char*)(gbase) + (voff)[_i]), (PG8_LAS unsigned*)(lds + (bufoff) + ldsw + _i * 8192), 16, 0, 0); } while (0)
; #define PG8_LDA(dst, b, h) do { _Pragma("unroll") for (int m = 0; m < 4; ++m) _Pragma("unroll") for (int k = 0; k < 2; ++k) dst[m][k] = *(const PG8_LAS bf16x8*)(lds + PG8_SA(b, h) + aoff + m * 2048 + k * 1024); } while (0)
; #define PG8_LDB(dst, b, h) do { _Pragma("unroll") for (int n = 0; n < 2; ++n) _Pragma("unroll") for (int k = 0; k < 2; ++k) dst[n][k] = *(const PG8_LAS bf16x8*)(lds + PG8_SB(b, h) + boff + n * 2048 + k * 1024); } while (0)
; #define PG8_MMA(ai, bj, At, Bt) do { __builtin_amdgcn_s_setprio(1); _Pragma("unroll") for (int m = 0; m < 4; ++m) _Pragma("unroll") for (int n = 0; n < 2; ++n) _Pragma("unroll") for (int k = 0; k < 2; ++k) \
;         acc[ai][bj][m][n] = __builtin_amdgcn_mfma_f32_16x16x32_bf16(Bt[n][k], At[m][k], acc[ai][bj][m][n], 0, 0, 0); __builtin_amdgcn_s_setprio(0); } while (0)
; #define PG8_WAIT_V(n) asm volatile("s_waitcnt vmcnt(" #n ")" ::: "memory")
; #define PG8_WAIT_L(n) asm volatile("s_waitcnt lgkmcnt(" #n ")" ::: "memory")
; #define PG8_BAR __builtin_amdgcn_s_barrier()
; template <class Epi, class Sched, bool ALIGN_EPI = false, bool SP2 = false, bool ACHUNK = false>
; __device__ __forceinline__ void gemm_phase(PG8_LAS unsigned char* lds, const Gemm g, const Sched& S, const Epi& E) {
;     ...
;             const char* a1 = cA + (size_t)(t + 1) * kstep;
;             const char* a2 = last ? nA : cA + (size_t)(t + 2) * kstep; const char* b2 = last ? nB : cB + (size_t)(t + 2) * kstep;
;             const char* a3 = a2 + kstep; const char* b3 = b2 + kstep;
;             if (last && has_next) S.a_ready(nxt);
;             if constexpr (SP2) {
;             PG8_LDB(B0, 0, 0); PG8_LDB(B1, 0, 1); PG8_SCHED; PG8_LDA(At, 0, 0); PG8_STAGE(PG8_SA(1, 1), a1 + hstepA, voffA);
;             PG8_WAIT_V(8); PG8_WAIT_L(0); PG8_BAR; PG8_MMA(0, 0, At, B0); PG8_MMA(0, 1, At, B1); PG8_BAR; PG8_SCHED;
;             PG8_LDA(At, 0, 1); PG8_STAGE(PG8_SB(0, 0), b2, voffB); PG8_STAGE(PG8_SB(0, 1), b2 + hstepB, voffB); PG8_STAGE(PG8_SA(0, 0), a2, voffA);
;             PG8_WAIT_V(8); PG8_WAIT_L(0); PG8_BAR; PG8_MMA(1, 0, At, B0); PG8_MMA(1, 1, At, B1); PG8_BAR; PG8_SCHED;
.LBB0_377:
	s_add_i32 s48, s6, 2
	s_add_u32 s49, s4, 0x80
	s_addc_u32 s7, s5, 0
	s_add_i32 s52, 0, 0x10000
	s_cmp_eq_u32 s27, s6
	s_cselect_b32 s7, s1, s7
	s_cselect_b32 s6, s0, s49
	v_add_u32_e32 v2, s52, v175
	s_cselect_b32 s51, s43, s9
	s_cselect_b32 s50, s42, s8
	s_add_i32 s49, 0, 0x14000
	s_waitcnt lgkmcnt(0)
	ds_read_b128 v[146:149], v2
	ds_read_b128 v[150:153], v2 offset:1024
	ds_read_b128 v[154:157], v2 offset:2048
	ds_read_b128 v[158:161], v2 offset:3072
	v_add_u32_e32 v2, s49, v175
	ds_read_b128 v[162:165], v2
	ds_read_b128 v[166:169], v2 offset:1024
	ds_read_b128 v[170:173], v2 offset:2048
	ds_read_b128 v[180:183], v2 offset:3072
	s_add_i32 m0, s20, 0xc000
	ds_read_b128 v[184:187], v179
	ds_read_b128 v[188:191], v179 offset:1024
	ds_read_b128 v[198:201], v179 offset:2048
	ds_read_b128 v[202:205], v179 offset:3072
	ds_read_b128 v[206:209], v179 offset:4096
	ds_read_b128 v[210:213], v179 offset:5120
	ds_read_b128 v[214:217], v179 offset:6144
	ds_read_b128 v[218:221], v179 offset:7168
	global_load_lds_dwordx4 v142, s[4:5]
	s_add_i32 m0, s20, 0xe000
	s_nop 0
	global_load_lds_dwordx4 v144, s[4:5]
	s_waitcnt vmcnt(8)
	s_waitcnt lgkmcnt(0)
	s_barrier
	s_setprio 1
	v_mfma_f32_16x16x32_bf16 v[124:127], v[146:149], v[184:187], v[124:127]
	v_mfma_f32_16x16x32_bf16 v[116:119], v[154:157], v[184:187], v[116:119]
	v_mfma_f32_16x16x32_bf16 v[108:111], v[146:149], v[198:201], v[108:111]
	v_mfma_f32_16x16x32_bf16 v[100:103], v[154:157], v[198:201], v[100:103]
	v_mfma_f32_16x16x32_bf16 v[92:95], v[146:149], v[206:209], v[92:95]
	v_mfma_f32_16x16x32_bf16 v[84:87], v[154:157], v[206:209], v[84:87]
	v_mfma_f32_16x16x32_bf16 v[76:79], v[146:149], v[214:217], v[76:79]
	v_mfma_f32_16x16x32_bf16 v[68:71], v[154:157], v[214:217], v[68:71]
	v_mfma_f32_16x16x32_bf16 v[124:127], v[150:153], v[188:191], v[124:127]
	v_mfma_f32_16x16x32_bf16 v[116:119], v[158:161], v[188:191], v[116:119]
	v_mfma_f32_16x16x32_bf16 v[108:111], v[150:153], v[202:205], v[108:111]
	v_mfma_f32_16x16x32_bf16 v[100:103], v[158:161], v[202:205], v[100:103]
	v_mfma_f32_16x16x32_bf16 v[92:95], v[150:153], v[210:213], v[92:95]
	v_mfma_f32_16x16x32_bf16 v[84:87], v[158:161], v[210:213], v[84:87]
	v_mfma_f32_16x16x32_bf16 v[76:79], v[150:153], v[218:221], v[76:79]
	v_mfma_f32_16x16x32_bf16 v[68:71], v[158:161], v[218:221], v[68:71]
	s_setprio 0
	s_setprio 1
	v_mfma_f32_16x16x32_bf16 v[128:131], v[162:165], v[184:187], v[128:131]
	v_mfma_f32_16x16x32_bf16 v[120:123], v[170:173], v[184:187], v[120:123]
	v_mfma_f32_16x16x32_bf16 v[112:115], v[162:165], v[198:201], v[112:115]
	v_mfma_f32_16x16x32_bf16 v[104:107], v[170:173], v[198:201], v[104:107]
	v_mfma_f32_16x16x32_bf16 v[96:99], v[162:165], v[206:209], v[96:99]
	v_mfma_f32_16x16x32_bf16 v[88:91], v[170:173], v[206:209], v[88:91]
	v_mfma_f32_16x16x32_bf16 v[80:83], v[162:165], v[214:217], v[80:83]
	v_mfma_f32_16x16x32_bf16 v[72:75], v[170:173], v[214:217], v[72:75]
	v_mfma_f32_16x16x32_bf16 v[128:131], v[166:169], v[188:191], v[128:131]
	v_mfma_f32_16x16x32_bf16 v[120:123], v[180:183], v[188:191], v[120:123]
	v_mfma_f32_16x16x32_bf16 v[112:115], v[166:169], v[202:205], v[112:115]
	v_mfma_f32_16x16x32_bf16 v[104:107], v[180:183], v[202:205], v[104:107]
	v_mfma_f32_16x16x32_bf16 v[96:99], v[166:169], v[210:213], v[96:99]
	v_mfma_f32_16x16x32_bf16 v[88:91], v[180:183], v[210:213], v[88:91]
	v_mfma_f32_16x16x32_bf16 v[80:83], v[166:169], v[218:221], v[80:83]
	v_mfma_f32_16x16x32_bf16 v[72:75], v[180:183], v[218:221], v[72:75]
	s_setprio 0
	s_barrier
	s_add_i32 s52, s52, s13
	s_mov_b32 m0, s52
	ds_read_b128 v[184:187], v179 offset:16384
	ds_read_b128 v[188:191], v179 offset:17408
	ds_read_b128 v[198:201], v179 offset:18432
	ds_read_b128 v[202:205], v179 offset:19456
	ds_read_b128 v[206:209], v179 offset:20480
	ds_read_b128 v[210:213], v179 offset:21504
	ds_read_b128 v[214:217], v179 offset:22528
	ds_read_b128 v[218:221], v179 offset:23552
	global_load_lds_dwordx4 v134, s[50:51]
	s_add_i32 m0, s52, 0x2000
	s_add_i32 s49, s49, s13
	global_load_lds_dwordx4 v138, s[50:51]
	s_add_u32 s50, s50, s18
	s_addc_u32 s51, s51, s19
	s_mov_b64 vcc, s[50:51]
	s_sub_u32 s98, s50, s18
	s_subb_u32 s99, s51, s19
	s_mov_b32 m0, s49
	s_nop 0
	global_load_lds_dwordx4 v134, s[50:51]
	s_add_i32 m0, s49, 0x2000
	s_nop 0
	global_load_lds_dwordx4 v138, s[50:51]
	s_mov_b32 m0, s20
	s_nop 0
	global_load_lds_dwordx4 v132, s[6:7]
	s_mov_b32 m0, s21
	s_nop 0
	global_load_lds_dwordx4 v136, s[6:7]
	s_waitcnt vmcnt(8)
	s_waitcnt lgkmcnt(0)
	s_barrier
	s_setprio 1
	v_mfma_f32_16x16x32_bf16 v[60:63], v[146:149], v[184:187], v[60:63]
	v_mfma_f32_16x16x32_bf16 v[52:55], v[154:157], v[184:187], v[52:55]
	v_mfma_f32_16x16x32_bf16 v[44:47], v[146:149], v[198:201], v[44:47]
	v_mfma_f32_16x16x32_bf16 v[36:39], v[154:157], v[198:201], v[36:39]
	v_mfma_f32_16x16x32_bf16 v[28:31], v[146:149], v[206:209], v[28:31]
	v_mfma_f32_16x16x32_bf16 v[20:23], v[154:157], v[206:209], v[20:23]
	v_mfma_f32_16x16x32_bf16 v[12:15], v[146:149], v[214:217], v[12:15]
	v_mfma_f32_16x16x32_bf16 v[4:7], v[154:157], v[214:217], v[4:7]
	v_mfma_f32_16x16x32_bf16 v[60:63], v[150:153], v[188:191], v[60:63]
	v_mfma_f32_16x16x32_bf16 v[52:55], v[158:161], v[188:191], v[52:55]
	v_mfma_f32_16x16x32_bf16 v[44:47], v[150:153], v[202:205], v[44:47]
	v_mfma_f32_16x16x32_bf16 v[36:39], v[158:161], v[202:205], v[36:39]
	v_mfma_f32_16x16x32_bf16 v[28:31], v[150:153], v[210:213], v[28:31]
	v_mfma_f32_16x16x32_bf16 v[20:23], v[158:161], v[210:213], v[20:23]
	v_mfma_f32_16x16x32_bf16 v[12:15], v[150:153], v[218:221], v[12:15]
	v_mfma_f32_16x16x32_bf16 v[4:7], v[158:161], v[218:221], v[4:7]
	s_setprio 0
	s_setprio 1
	v_mfma_f32_16x16x32_bf16 v[64:67], v[162:165], v[184:187], v[64:67]
	v_mfma_f32_16x16x32_bf16 v[56:59], v[170:173], v[184:187], v[56:59]
	v_mfma_f32_16x16x32_bf16 v[48:51], v[162:165], v[198:201], v[48:51]
	v_mfma_f32_16x16x32_bf16 v[40:43], v[170:173], v[198:201], v[40:43]
	v_mfma_f32_16x16x32_bf16 v[32:35], v[162:165], v[206:209], v[32:35]
	v_mfma_f32_16x16x32_bf16 v[24:27], v[170:173], v[206:209], v[24:27]
	v_mfma_f32_16x16x32_bf16 v[16:19], v[162:165], v[214:217], v[16:19]
	v_mfma_f32_16x16x32_bf16 v[8:11], v[170:173], v[214:217], v[8:11]
	v_mfma_f32_16x16x32_bf16 v[64:67], v[166:169], v[188:191], v[64:67]
	v_mfma_f32_16x16x32_bf16 v[56:59], v[180:183], v[188:191], v[56:59]
	v_mfma_f32_16x16x32_bf16 v[48:51], v[166:169], v[202:205], v[48:51]
	v_mfma_f32_16x16x32_bf16 v[40:43], v[180:183], v[202:205], v[40:43]
	v_mfma_f32_16x16x32_bf16 v[32:35], v[166:169], v[210:213], v[32:35]
	v_mfma_f32_16x16x32_bf16 v[24:27], v[180:183], v[210:213], v[24:27]
	v_mfma_f32_16x16x32_bf16 v[16:19], v[166:169], v[218:221], v[16:19]
	v_mfma_f32_16x16x32_bf16 v[8:11], v[180:183], v[218:221], v[8:11]
	s_setprio 0
	s_barrier
; #define PG8_STAGE(bufoff, gbase, voff) do { _Pragma("unroll") for (int _i = 0; _i < 2; ++_i) \
;         __builtin_amdgcn_global_load_lds((const unsigned*)((const char*)(gbase) + (voff)[_i]), (PG8_LAS unsigned*)(lds + (bufoff) + ldsw + _i * 8192), 16, 0, 0); } while (0)
; #define PG8_LDA(dst, b, h) do { _Pragma("unroll") for (int m = 0; m < 4; ++m) _Pragma("unroll") for (int k = 0; k < 2; ++k) dst[m][k] = *(const PG8_LAS bf16x8*)(lds + PG8_SA(b, h) + aoff + m * 2048 + k * 1024); } while (0)
; #define PG8_LDB(dst, b, h) do { _Pragma("unroll") for (int n = 0; n < 2; ++n) _Pragma("unroll") for (int k = 0; k < 2; ++k) dst[n][k] = *(const PG8_LAS bf16x8*)(lds + PG8_SB(b, h) + boff + n * 2048 + k * 1024); } while (0)
; #define PG8_MMA(ai, bj, At, Bt) do { __builtin_amdgcn_s_setprio(1); _Pragma("unroll") for (int m = 0; m < 4; ++m) _Pragma("unroll") for (int n = 0; n < 2; ++n) _Pragma("unroll") for (int k = 0; k < 2; ++k) \
;         acc[ai][bj][m][n] = __builtin_amdgcn_mfma_f32_16x16x32_bf16(Bt[n][k], At[m][k], acc[ai][bj][m][n], 0, 0, 0); __builtin_amdgcn_s_setprio(0); } while (0)
; #define PG8_WAIT_V(n) asm volatile("s_waitcnt vmcnt(" #n ")" ::: "memory")
; #define PG8_WAIT_L(n) asm volatile("s_waitcnt lgkmcnt(" #n ")" ::: "memory")
; #define PG8_BAR __builtin_amdgcn_s_barrier()
; #define PG8_SCHED __builtin_amdgcn_sched_barrier(0)
; template <class Epi, class Sched, bool ALIGN_EPI = false, bool SP2 = false, bool ACHUNK = false>
; __device__ __forceinline__ void gemm_phase(PG8_LAS unsigned char* lds, const Gemm g, const Sched& S, const Epi& E) {
;     ...
;             PG8_LDB(B0, 1, 0); PG8_LDB(B1, 1, 1); PG8_SCHED; PG8_LDA(At, 1, 0); PG8_STAGE(PG8_SA(0, 1), a2 + hstepA, voffA);
;             PG8_WAIT_V(8); PG8_WAIT_L(0); PG8_BAR; PG8_MMA(0, 0, At, B0); PG8_MMA(0, 1, At, B1); PG8_BAR; PG8_SCHED;
;             PG8_LDA(At, 1, 1); PG8_STAGE(PG8_SB(1, 0), b3, voffB); PG8_STAGE(PG8_SB(1, 1), b3 + hstepB, voffB); PG8_STAGE(PG8_SA(1, 0), a3, voffA);
;             PG8_WAIT_V(8); PG8_WAIT_L(0); PG8_BAR; PG8_MMA(1, 0, At, B0); PG8_MMA(1, 1, At, B1); PG8_BAR; PG8_SCHED;
	s_add_i32 s49, 0, 0x18000
	v_add_u32_e32 v2, s49, v175
	s_add_i32 s50, 0, 0x1c000
	ds_read_b128 v[146:149], v2
	ds_read_b128 v[150:153], v2 offset:1024
	ds_read_b128 v[154:157], v2 offset:2048
	ds_read_b128 v[158:161], v2 offset:3072
	v_add_u32_e32 v2, s50, v175
	ds_read_b128 v[162:165], v2
	ds_read_b128 v[166:169], v2 offset:1024
	ds_read_b128 v[170:173], v2 offset:2048
	ds_read_b128 v[180:183], v2 offset:3072
	s_add_u32 s6, s6, s18
	s_addc_u32 s7, s7, s19
	s_mov_b32 m0, s22
	ds_read_b128 v[184:187], v179 offset:32768
	ds_read_b128 v[188:191], v179 offset:33792
	ds_read_b128 v[198:201], v179 offset:34816
	ds_read_b128 v[202:205], v179 offset:35840
	ds_read_b128 v[206:209], v179 offset:36864
	ds_read_b128 v[210:213], v179 offset:37888
	ds_read_b128 v[214:217], v179 offset:38912
	ds_read_b128 v[218:221], v179 offset:39936
	global_load_lds_dwordx4 v132, s[6:7]
	s_mov_b32 m0, s23
	s_nop 0
	global_load_lds_dwordx4 v136, s[6:7]
	s_waitcnt vmcnt(8)
	s_waitcnt lgkmcnt(0)
	s_barrier
	s_setprio 1
	v_mfma_f32_16x16x32_bf16 v[124:127], v[146:149], v[184:187], v[124:127]
	v_mfma_f32_16x16x32_bf16 v[116:119], v[154:157], v[184:187], v[116:119]
	v_mfma_f32_16x16x32_bf16 v[108:111], v[146:149], v[198:201], v[108:111]
	v_mfma_f32_16x16x32_bf16 v[100:103], v[154:157], v[198:201], v[100:103]
	v_mfma_f32_16x16x32_bf16 v[92:95], v[146:149], v[206:209], v[92:95]
	v_mfma_f32_16x16x32_bf16 v[84:87], v[154:157], v[206:209], v[84:87]
	v_mfma_f32_16x16x32_bf16 v[76:79], v[146:149], v[214:217], v[76:79]
	v_mfma_f32_16x16x32_bf16 v[68:71], v[154:157], v[214:217], v[68:71]
	v_mfma_f32_16x16x32_bf16 v[124:127], v[150:153], v[188:191], v[124:127]
	v_mfma_f32_16x16x32_bf16 v[116:119], v[158:161], v[188:191], v[116:119]
	v_mfma_f32_16x16x32_bf16 v[108:111], v[150:153], v[202:205], v[108:111]
	v_mfma_f32_16x16x32_bf16 v[100:103], v[158:161], v[202:205], v[100:103]
	v_mfma_f32_16x16x32_bf16 v[92:95], v[150:153], v[210:213], v[92:95]
	v_mfma_f32_16x16x32_bf16 v[84:87], v[158:161], v[210:213], v[84:87]
	v_mfma_f32_16x16x32_bf16 v[76:79], v[150:153], v[218:221], v[76:79]
	v_mfma_f32_16x16x32_bf16 v[68:71], v[158:161], v[218:221], v[68:71]
	s_setprio 0
	s_setprio 1
	v_mfma_f32_16x16x32_bf16 v[128:131], v[162:165], v[184:187], v[128:131]
	v_mfma_f32_16x16x32_bf16 v[120:123], v[170:173], v[184:187], v[120:123]
	v_mfma_f32_16x16x32_bf16 v[112:115], v[162:165], v[198:201], v[112:115]
	v_mfma_f32_16x16x32_bf16 v[104:107], v[170:173], v[198:201], v[104:107]
	v_mfma_f32_16x16x32_bf16 v[96:99], v[162:165], v[206:209], v[96:99]
	v_mfma_f32_16x16x32_bf16 v[88:91], v[170:173], v[206:209], v[88:91]
	v_mfma_f32_16x16x32_bf16 v[80:83], v[162:165], v[214:217], v[80:83]
	v_mfma_f32_16x16x32_bf16 v[72:75], v[170:173], v[214:217], v[72:75]
	v_mfma_f32_16x16x32_bf16 v[128:131], v[166:169], v[188:191], v[128:131]
	v_mfma_f32_16x16x32_bf16 v[120:123], v[180:183], v[188:191], v[120:123]
	v_mfma_f32_16x16x32_bf16 v[112:115], v[166:169], v[202:205], v[112:115]
	v_mfma_f32_16x16x32_bf16 v[104:107], v[180:183], v[202:205], v[104:107]
	v_mfma_f32_16x16x32_bf16 v[96:99], v[166:169], v[210:213], v[96:99]
	v_mfma_f32_16x16x32_bf16 v[88:91], v[180:183], v[210:213], v[88:91]
	v_mfma_f32_16x16x32_bf16 v[80:83], v[166:169], v[218:221], v[80:83]
	v_mfma_f32_16x16x32_bf16 v[72:75], v[180:183], v[218:221], v[72:75]
	s_setprio 0
	s_barrier
	s_add_u32 vcc_lo, vcc_lo, s10
	s_addc_u32 vcc_hi, vcc_hi, s11
	s_add_u32 s98, s98, s10
	s_addc_u32 s99, s99, s11
	s_sub_u32 s6, s6, s18
	s_subb_u32 s7, s7, s19
	s_add_u32 s6, s6, s10
	s_addc_u32 s7, s7, s11
	s_add_i32 m0, s49, s13
	ds_read_b128 v[184:187], v179 offset:49152
	ds_read_b128 v[188:191], v179 offset:50176
	ds_read_b128 v[198:201], v179 offset:51200
	ds_read_b128 v[202:205], v179 offset:52224
	ds_read_b128 v[206:209], v179 offset:53248
	ds_read_b128 v[210:213], v179 offset:54272
	ds_read_b128 v[214:217], v179 offset:55296
	ds_read_b128 v[218:221], v179 offset:56320
	global_load_lds_dwordx4 v134, s[98:99]
	s_add_i32 m0, m0, 0x2000
	s_nop 0
	global_load_lds_dwordx4 v138, s[98:99]
	s_add_i32 m0, s50, s13
	s_nop 0
	global_load_lds_dwordx4 v134, vcc
	s_add_i32 m0, m0, 0x2000
	s_nop 0
	global_load_lds_dwordx4 v138, vcc
	s_mov_b32 m0, s25
	s_nop 0
	global_load_lds_dwordx4 v132, s[6:7]
	s_mov_b32 m0, s26
	s_nop 0
	global_load_lds_dwordx4 v136, s[6:7]
	s_waitcnt vmcnt(8)
	s_waitcnt lgkmcnt(0)
	s_barrier
	s_setprio 1
	v_mfma_f32_16x16x32_bf16 v[60:63], v[146:149], v[184:187], v[60:63]
	v_mfma_f32_16x16x32_bf16 v[52:55], v[154:157], v[184:187], v[52:55]
	v_mfma_f32_16x16x32_bf16 v[44:47], v[146:149], v[198:201], v[44:47]
	v_mfma_f32_16x16x32_bf16 v[36:39], v[154:157], v[198:201], v[36:39]
	v_mfma_f32_16x16x32_bf16 v[28:31], v[146:149], v[206:209], v[28:31]
	v_mfma_f32_16x16x32_bf16 v[20:23], v[154:157], v[206:209], v[20:23]
	v_mfma_f32_16x16x32_bf16 v[12:15], v[146:149], v[214:217], v[12:15]
	v_mfma_f32_16x16x32_bf16 v[4:7], v[154:157], v[214:217], v[4:7]
	v_mfma_f32_16x16x32_bf16 v[60:63], v[150:153], v[188:191], v[60:63]
	v_mfma_f32_16x16x32_bf16 v[52:55], v[158:161], v[188:191], v[52:55]
	v_mfma_f32_16x16x32_bf16 v[44:47], v[150:153], v[202:205], v[44:47]
	v_mfma_f32_16x16x32_bf16 v[36:39], v[158:161], v[202:205], v[36:39]
	v_mfma_f32_16x16x32_bf16 v[28:31], v[150:153], v[210:213], v[28:31]
	v_mfma_f32_16x16x32_bf16 v[20:23], v[158:161], v[210:213], v[20:23]
	v_mfma_f32_16x16x32_bf16 v[12:15], v[150:153], v[218:221], v[12:15]
	v_mfma_f32_16x16x32_bf16 v[4:7], v[158:161], v[218:221], v[4:7]
	s_setprio 0
	s_setprio 1
	v_mfma_f32_16x16x32_bf16 v[64:67], v[162:165], v[184:187], v[64:67]
	v_mfma_f32_16x16x32_bf16 v[56:59], v[170:173], v[184:187], v[56:59]
	v_mfma_f32_16x16x32_bf16 v[48:51], v[162:165], v[198:201], v[48:51]
	v_mfma_f32_16x16x32_bf16 v[40:43], v[170:173], v[198:201], v[40:43]
	v_mfma_f32_16x16x32_bf16 v[32:35], v[162:165], v[206:209], v[32:35]
	v_mfma_f32_16x16x32_bf16 v[24:27], v[170:173], v[206:209], v[24:27]
	v_mfma_f32_16x16x32_bf16 v[16:19], v[162:165], v[214:217], v[16:19]
	v_mfma_f32_16x16x32_bf16 v[8:11], v[170:173], v[214:217], v[8:11]
	v_mfma_f32_16x16x32_bf16 v[64:67], v[166:169], v[188:191], v[64:67]
	v_mfma_f32_16x16x32_bf16 v[56:59], v[180:183], v[188:191], v[56:59]
	v_mfma_f32_16x16x32_bf16 v[48:51], v[166:169], v[202:205], v[48:51]
	v_mfma_f32_16x16x32_bf16 v[40:43], v[180:183], v[202:205], v[40:43]
	v_mfma_f32_16x16x32_bf16 v[32:35], v[166:169], v[210:213], v[32:35]
	v_mfma_f32_16x16x32_bf16 v[24:27], v[180:183], v[210:213], v[24:27]
	v_mfma_f32_16x16x32_bf16 v[16:19], v[166:169], v[218:221], v[16:19]
	v_mfma_f32_16x16x32_bf16 v[8:11], v[180:183], v[218:221], v[8:11]
	s_setprio 0
	s_barrier
	s_add_u32 s4, s4, 0x100
	s_addc_u32 s5, s5, 0
	s_add_u32 s8, s8, 0x100
	s_addc_u32 s9, s9, 0
	s_cmp_ge_i32 s48, s24
	s_mov_b32 s6, s48
	s_cbranch_scc0 .LBB0_377
	v_readlane_b32 s52, v254, 27
	v_readlane_b32 s53, v254, 28
	s_mov_b32 s50, s94

; #define PG8_STAGE(bufoff, gbase, voff) do { _Pragma("unroll") for (int _i = 0; _i < 2; ++_i) \
;         __builtin_amdgcn_global_load_lds((const unsigned*)((const char*)(gbase) + (voff)[_i]), (PG8_LAS unsigned*)(lds + (bufoff) + ldsw + _i * 8192), 16, 0, 0); } while (0)
; #define PG8_LDA(dst, b, h) do { _Pragma("unroll") for (int m = 0; m < 4; ++m) _Pragma("unroll") for (int k = 0; k < 2; ++k) dst[m][k] = *(const PG8_LAS bf16x8*)(lds + PG8_SA(b, h) + aoff + m * 2048 + k * 1024); } while (0)
; #define PG8_LDB(dst, b, h) do { _Pragma("unroll") for (int n = 0; n < 2; ++n) _Pragma("unroll") for (int k = 0; k < 2; ++k) dst[n][k] = *(const PG8_LAS bf16x8*)(lds + PG8_SB(b, h) + boff + n * 2048 + k * 1024); } while (0)
; #define PG8_MMA(ai, bj, At, Bt) do { __builtin_amdgcn_s_setprio(1); _Pragma("unroll") for (int m = 0; m < 4; ++m) _Pragma("unroll") for (int n = 0; n < 2; ++n) _Pragma("unroll") for (int k = 0; k < 2; ++k) \
;         acc[ai][bj][m][n] = __builtin_amdgcn_mfma_f32_16x16x32_bf16(Bt[n][k], At[m][k], acc[ai][bj][m][n], 0, 0, 0); __builtin_amdgcn_s_setprio(0); } while (0)
; #define PG8_WAIT_V(n) asm volatile("s_waitcnt vmcnt(" #n ")" ::: "memory")
; #define PG8_WAIT_L(n) asm volatile("s_waitcnt lgkmcnt(" #n ")" ::: "memory")
; #define PG8_BAR __builtin_amdgcn_s_barrier()
; #define PG8_SCHED __builtin_amdgcn_sched_barrier(0)
; template <class Epi, class Sched, bool ALIGN_EPI = false, bool SP2 = false, bool ACHUNK = false>
; __device__ __forceinline__ void gemm_phase(PG8_LAS unsigned char* lds, const Gemm g, const Sched& S, const Epi& E) {
;     ...
;             PG8_LDB(B0, 0, 0); PG8_LDB(B1, 0, 1); PG8_SCHED; PG8_LDA(At, 0, 0); PG8_STAGE(PG8_SA(1, 1), a1 + hstepA, voffA);
;             PG8_WAIT_V(8); PG8_WAIT_L(0); PG8_BAR; PG8_MMA(0, 0, At, B0); PG8_MMA(0, 1, At, B1); PG8_BAR; PG8_SCHED;
;             PG8_LDA(At, 0, 1); PG8_STAGE(PG8_SB(0, 0), b2, voffB); PG8_STAGE(PG8_SB(0, 1), b2 + hstepB, voffB); PG8_STAGE(PG8_SA(0, 0), a2, voffA);
;             PG8_WAIT_V(8); PG8_WAIT_L(0); PG8_BAR; PG8_MMA(1, 0, At, B0); PG8_MMA(1, 1, At, B1); PG8_BAR; PG8_SCHED;
.Lnl_pl:
	s_add_i32 s9, 0, 0x14000
	v_add_u32_e32 v144, s15, v221
	v_add_u32_e32 v160, s9, v221
	ds_read_b128 v[132:135], v144
	ds_read_b128 v[136:139], v144 offset:1024
	ds_read_b128 v[140:143], v144 offset:2048
	ds_read_b128 v[144:147], v144 offset:3072
	ds_read_b128 v[148:151], v160
	ds_read_b128 v[152:155], v160 offset:1024
	ds_read_b128 v[156:159], v160 offset:2048
	ds_read_b128 v[160:163], v160 offset:3072
	s_add_i32 m0, s27, 0xc000
	ds_read_b128 v[178:181], v223
	ds_read_b128 v[182:185], v223 offset:1024
	ds_read_b128 v[186:189], v223 offset:2048
	ds_read_b128 v[190:193], v223 offset:3072
	ds_read_b128 v[198:201], v223 offset:4096
	ds_read_b128 v[202:205], v223 offset:5120
	ds_read_b128 v[206:209], v223 offset:6144
	ds_read_b128 v[210:213], v223 offset:7168
	global_load_lds_dwordx4 v174, s[0:1]
	s_add_i32 m0, s27, 0xe000
	s_nop 0
	global_load_lds_dwordx4 v176, s[0:1]
	s_waitcnt vmcnt(8)
	s_waitcnt lgkmcnt(0)
	s_barrier
	s_setprio 1
	v_mfma_f32_16x16x32_bf16 v[128:131], v[132:135], v[178:181], v[128:131]
	v_mfma_f32_16x16x32_bf16 v[124:127], v[140:143], v[178:181], v[124:127]
	v_mfma_f32_16x16x32_bf16 v[112:115], v[132:135], v[186:189], v[112:115]
	v_mfma_f32_16x16x32_bf16 v[108:111], v[140:143], v[186:189], v[108:111]
	v_mfma_f32_16x16x32_bf16 v[96:99], v[132:135], v[198:201], v[96:99]
	v_mfma_f32_16x16x32_bf16 v[92:95], v[140:143], v[198:201], v[92:95]
	v_mfma_f32_16x16x32_bf16 v[80:83], v[132:135], v[206:209], v[80:83]
	v_mfma_f32_16x16x32_bf16 v[76:79], v[140:143], v[206:209], v[76:79]
	v_mfma_f32_16x16x32_bf16 v[128:131], v[136:139], v[182:185], v[128:131]
	v_mfma_f32_16x16x32_bf16 v[124:127], v[144:147], v[182:185], v[124:127]
	v_mfma_f32_16x16x32_bf16 v[112:115], v[136:139], v[190:193], v[112:115]
	v_mfma_f32_16x16x32_bf16 v[108:111], v[144:147], v[190:193], v[108:111]
	v_mfma_f32_16x16x32_bf16 v[96:99], v[136:139], v[202:205], v[96:99]
	v_mfma_f32_16x16x32_bf16 v[92:95], v[144:147], v[202:205], v[92:95]
	v_mfma_f32_16x16x32_bf16 v[80:83], v[136:139], v[210:213], v[80:83]
	v_mfma_f32_16x16x32_bf16 v[76:79], v[144:147], v[210:213], v[76:79]
	s_setprio 0
	s_setprio 1
	v_mfma_f32_16x16x32_bf16 v[120:123], v[148:151], v[178:181], v[120:123]
	v_mfma_f32_16x16x32_bf16 v[116:119], v[156:159], v[178:181], v[116:119]
	v_mfma_f32_16x16x32_bf16 v[104:107], v[148:151], v[186:189], v[104:107]
	v_mfma_f32_16x16x32_bf16 v[100:103], v[156:159], v[186:189], v[100:103]
	v_mfma_f32_16x16x32_bf16 v[88:91], v[148:151], v[198:201], v[88:91]
	v_mfma_f32_16x16x32_bf16 v[84:87], v[156:159], v[198:201], v[84:87]
	v_mfma_f32_16x16x32_bf16 v[72:75], v[148:151], v[206:209], v[72:75]
	v_mfma_f32_16x16x32_bf16 v[68:71], v[156:159], v[206:209], v[68:71]
	v_mfma_f32_16x16x32_bf16 v[120:123], v[152:155], v[182:185], v[120:123]
	v_mfma_f32_16x16x32_bf16 v[116:119], v[160:163], v[182:185], v[116:119]
	v_mfma_f32_16x16x32_bf16 v[104:107], v[152:155], v[190:193], v[104:107]
	v_mfma_f32_16x16x32_bf16 v[100:103], v[160:163], v[190:193], v[100:103]
	v_mfma_f32_16x16x32_bf16 v[88:91], v[152:155], v[202:205], v[88:91]
	v_mfma_f32_16x16x32_bf16 v[84:87], v[160:163], v[202:205], v[84:87]
	v_mfma_f32_16x16x32_bf16 v[72:75], v[152:155], v[210:213], v[72:75]
	v_mfma_f32_16x16x32_bf16 v[68:71], v[160:163], v[210:213], v[68:71]
	s_setprio 0
	s_barrier
	s_add_i32 s15, s15, s26
	s_mov_b32 m0, s15
	ds_read_b128 v[178:181], v223 offset:16384
	ds_read_b128 v[182:185], v223 offset:17408
	ds_read_b128 v[186:189], v223 offset:18432
	ds_read_b128 v[190:193], v223 offset:19456
	ds_read_b128 v[198:201], v223 offset:20480
	ds_read_b128 v[202:205], v223 offset:21504
	ds_read_b128 v[206:209], v223 offset:22528
	ds_read_b128 v[210:213], v223 offset:23552
	global_load_lds_dwordx4 v2, s[16:17]
	s_add_i32 m0, s15, 0x2000
	s_add_i32 s9, s9, s26
	global_load_lds_dwordx4 v168, s[16:17]
	s_add_u32 s16, s16, s18
	s_addc_u32 s17, s17, s19
	s_mov_b64 vcc, s[16:17]
	s_sub_u32 s98, s16, s18
	s_subb_u32 s99, s17, s19
	s_mov_b32 m0, s9
	s_nop 0
	global_load_lds_dwordx4 v2, s[16:17]
	s_add_i32 m0, s9, 0x2000
	s_nop 0
	global_load_lds_dwordx4 v168, s[16:17]
	s_mov_b32 m0, s27
	s_nop 0
	global_load_lds_dwordx4 v164, s[4:5]
	s_mov_b32 m0, s36
	s_nop 0
	global_load_lds_dwordx4 v166, s[4:5]
	s_waitcnt vmcnt(8)
	s_waitcnt lgkmcnt(0)
	s_barrier
	s_setprio 1
	v_mfma_f32_16x16x32_bf16 v[64:67], v[132:135], v[178:181], v[64:67]
	v_mfma_f32_16x16x32_bf16 v[60:63], v[140:143], v[178:181], v[60:63]
	v_mfma_f32_16x16x32_bf16 v[48:51], v[132:135], v[186:189], v[48:51]
	v_mfma_f32_16x16x32_bf16 v[44:47], v[140:143], v[186:189], v[44:47]
	v_mfma_f32_16x16x32_bf16 v[32:35], v[132:135], v[198:201], v[32:35]
	v_mfma_f32_16x16x32_bf16 v[28:31], v[140:143], v[198:201], v[28:31]
	v_mfma_f32_16x16x32_bf16 v[16:19], v[132:135], v[206:209], v[16:19]
	v_mfma_f32_16x16x32_bf16 v[12:15], v[140:143], v[206:209], v[12:15]
	v_mfma_f32_16x16x32_bf16 v[64:67], v[136:139], v[182:185], v[64:67]
	v_mfma_f32_16x16x32_bf16 v[60:63], v[144:147], v[182:185], v[60:63]
	v_mfma_f32_16x16x32_bf16 v[48:51], v[136:139], v[190:193], v[48:51]
	v_mfma_f32_16x16x32_bf16 v[44:47], v[144:147], v[190:193], v[44:47]
	v_mfma_f32_16x16x32_bf16 v[32:35], v[136:139], v[202:205], v[32:35]
	v_mfma_f32_16x16x32_bf16 v[28:31], v[144:147], v[202:205], v[28:31]
	v_mfma_f32_16x16x32_bf16 v[16:19], v[136:139], v[210:213], v[16:19]
	v_mfma_f32_16x16x32_bf16 v[12:15], v[144:147], v[210:213], v[12:15]
	s_setprio 0
	s_setprio 1
	v_mfma_f32_16x16x32_bf16 v[56:59], v[148:151], v[178:181], v[56:59]
	v_mfma_f32_16x16x32_bf16 v[52:55], v[156:159], v[178:181], v[52:55]
	v_mfma_f32_16x16x32_bf16 v[40:43], v[148:151], v[186:189], v[40:43]
	v_mfma_f32_16x16x32_bf16 v[36:39], v[156:159], v[186:189], v[36:39]
	v_mfma_f32_16x16x32_bf16 v[24:27], v[148:151], v[198:201], v[24:27]
	v_mfma_f32_16x16x32_bf16 v[20:23], v[156:159], v[198:201], v[20:23]
	v_mfma_f32_16x16x32_bf16 v[8:11], v[148:151], v[206:209], v[8:11]
	v_mfma_f32_16x16x32_bf16 v[4:7], v[156:159], v[206:209], v[4:7]
	v_mfma_f32_16x16x32_bf16 v[56:59], v[152:155], v[182:185], v[56:59]
	v_mfma_f32_16x16x32_bf16 v[52:55], v[160:163], v[182:185], v[52:55]
	v_mfma_f32_16x16x32_bf16 v[40:43], v[152:155], v[190:193], v[40:43]
	v_mfma_f32_16x16x32_bf16 v[36:39], v[160:163], v[190:193], v[36:39]
	v_mfma_f32_16x16x32_bf16 v[24:27], v[152:155], v[202:205], v[24:27]
	v_mfma_f32_16x16x32_bf16 v[20:23], v[160:163], v[202:205], v[20:23]
	v_mfma_f32_16x16x32_bf16 v[8:11], v[152:155], v[210:213], v[8:11]
	v_mfma_f32_16x16x32_bf16 v[4:7], v[160:163], v[210:213], v[4:7]
	s_setprio 0
	s_barrier
; #define PG8_STAGE(bufoff, gbase, voff) do { _Pragma("unroll") for (int _i = 0; _i < 2; ++_i) \
;         __builtin_amdgcn_global_load_lds((const unsigned*)((const char*)(gbase) + (voff)[_i]), (PG8_LAS unsigned*)(lds + (bufoff) + ldsw + _i * 8192), 16, 0, 0); } while (0)
; #define PG8_LDA(dst, b, h) do { _Pragma("unroll") for (int m = 0; m < 4; ++m) _Pragma("unroll") for (int k = 0; k < 2; ++k) dst[m][k] = *(const PG8_LAS bf16x8*)(lds + PG8_SA(b, h) + aoff + m * 2048 + k * 1024); } while (0)
; #define PG8_LDB(dst, b, h) do { _Pragma("unroll") for (int n = 0; n < 2; ++n) _Pragma("unroll") for (int k = 0; k < 2; ++k) dst[n][k] = *(const PG8_LAS bf16x8*)(lds + PG8_SB(b, h) + boff + n * 2048 + k * 1024); } while (0)
; #define PG8_MMA(ai, bj, At, Bt) do { __builtin_amdgcn_s_setprio(1); _Pragma("unroll") for (int m = 0; m < 4; ++m) _Pragma("unroll") for (int n = 0; n < 2; ++n) _Pragma("unroll") for (int k = 0; k < 2; ++k) \
;         acc[ai][bj][m][n] = __builtin_amdgcn_mfma_f32_16x16x32_bf16(Bt[n][k], At[m][k], acc[ai][bj][m][n], 0, 0, 0); __builtin_amdgcn_s_setprio(0); } while (0)
; #define PG8_WAIT_V(n) asm volatile("s_waitcnt vmcnt(" #n ")" ::: "memory")
; #define PG8_WAIT_L(n) asm volatile("s_waitcnt lgkmcnt(" #n ")" ::: "memory")
; #define PG8_BAR __builtin_amdgcn_s_barrier()
; #define PG8_SCHED __builtin_amdgcn_sched_barrier(0)
; template <class Epi, class Sched, bool ALIGN_EPI = false, bool SP2 = false, bool ACHUNK = false>
; __device__ __forceinline__ void gemm_phase(PG8_LAS unsigned char* lds, const Gemm g, const Sched& S, const Epi& E) {
;     ...
;             PG8_LDB(B0, 1, 0); PG8_LDB(B1, 1, 1); PG8_SCHED; PG8_LDA(At, 1, 0); PG8_STAGE(PG8_SA(0, 1), a2 + hstepA, voffA);
;             PG8_WAIT_V(8); PG8_WAIT_L(0); PG8_BAR; PG8_MMA(0, 0, At, B0); PG8_MMA(0, 1, At, B1); PG8_BAR; PG8_SCHED;
;             PG8_LDA(At, 1, 1); PG8_STAGE(PG8_SB(1, 0), b3, voffB); PG8_STAGE(PG8_SB(1, 1), b3 + hstepB, voffB); PG8_STAGE(PG8_SA(1, 0), a3, voffA);
;             PG8_WAIT_V(8); PG8_WAIT_L(0); PG8_BAR; PG8_MMA(1, 0, At, B0); PG8_MMA(1, 1, At, B1); PG8_BAR; PG8_SCHED;
	s_add_i32 s9, 0, 0x18000
	s_add_i32 s15, 0, 0x1c000
	v_add_u32_e32 v144, s9, v221
	v_add_u32_e32 v160, s15, v221
	ds_read_b128 v[132:135], v144
	ds_read_b128 v[136:139], v144 offset:1024
	ds_read_b128 v[140:143], v144 offset:2048
	ds_read_b128 v[144:147], v144 offset:3072
	ds_read_b128 v[148:151], v160
	ds_read_b128 v[152:155], v160 offset:1024
	ds_read_b128 v[156:159], v160 offset:2048
	ds_read_b128 v[160:163], v160 offset:3072
	s_add_u32 s4, s4, s18
	s_addc_u32 s5, s5, s19
	s_mov_b32 m0, s37
	ds_read_b128 v[178:181], v223 offset:32768
	ds_read_b128 v[182:185], v223 offset:33792
	ds_read_b128 v[186:189], v223 offset:34816
	ds_read_b128 v[190:193], v223 offset:35840
	ds_read_b128 v[198:201], v223 offset:36864
	ds_read_b128 v[202:205], v223 offset:37888
	ds_read_b128 v[206:209], v223 offset:38912
	ds_read_b128 v[210:213], v223 offset:39936
	global_load_lds_dwordx4 v164, s[4:5]
	s_mov_b32 m0, s76
	s_nop 0
	global_load_lds_dwordx4 v166, s[4:5]
	s_waitcnt vmcnt(8)
	s_waitcnt lgkmcnt(0)
	s_barrier
	s_setprio 1
	v_mfma_f32_16x16x32_bf16 v[128:131], v[132:135], v[178:181], v[128:131]
	v_mfma_f32_16x16x32_bf16 v[124:127], v[140:143], v[178:181], v[124:127]
	v_mfma_f32_16x16x32_bf16 v[112:115], v[132:135], v[186:189], v[112:115]
	v_mfma_f32_16x16x32_bf16 v[108:111], v[140:143], v[186:189], v[108:111]
	v_mfma_f32_16x16x32_bf16 v[96:99], v[132:135], v[198:201], v[96:99]
	v_mfma_f32_16x16x32_bf16 v[92:95], v[140:143], v[198:201], v[92:95]
	v_mfma_f32_16x16x32_bf16 v[80:83], v[132:135], v[206:209], v[80:83]
	v_mfma_f32_16x16x32_bf16 v[76:79], v[140:143], v[206:209], v[76:79]
	v_mfma_f32_16x16x32_bf16 v[128:131], v[136:139], v[182:185], v[128:131]
	v_mfma_f32_16x16x32_bf16 v[124:127], v[144:147], v[182:185], v[124:127]
	v_mfma_f32_16x16x32_bf16 v[112:115], v[136:139], v[190:193], v[112:115]
	v_mfma_f32_16x16x32_bf16 v[108:111], v[144:147], v[190:193], v[108:111]
	v_mfma_f32_16x16x32_bf16 v[96:99], v[136:139], v[202:205], v[96:99]
	v_mfma_f32_16x16x32_bf16 v[92:95], v[144:147], v[202:205], v[92:95]
	v_mfma_f32_16x16x32_bf16 v[80:83], v[136:139], v[210:213], v[80:83]
	v_mfma_f32_16x16x32_bf16 v[76:79], v[144:147], v[210:213], v[76:79]
	s_setprio 0
	s_setprio 1
	v_mfma_f32_16x16x32_bf16 v[120:123], v[148:151], v[178:181], v[120:123]
	v_mfma_f32_16x16x32_bf16 v[116:119], v[156:159], v[178:181], v[116:119]
	v_mfma_f32_16x16x32_bf16 v[104:107], v[148:151], v[186:189], v[104:107]
	v_mfma_f32_16x16x32_bf16 v[100:103], v[156:159], v[186:189], v[100:103]
	v_mfma_f32_16x16x32_bf16 v[88:91], v[148:151], v[198:201], v[88:91]
	v_mfma_f32_16x16x32_bf16 v[84:87], v[156:159], v[198:201], v[84:87]
	v_mfma_f32_16x16x32_bf16 v[72:75], v[148:151], v[206:209], v[72:75]
	v_mfma_f32_16x16x32_bf16 v[68:71], v[156:159], v[206:209], v[68:71]
	v_mfma_f32_16x16x32_bf16 v[120:123], v[152:155], v[182:185], v[120:123]
	v_mfma_f32_16x16x32_bf16 v[116:119], v[160:163], v[182:185], v[116:119]
	v_mfma_f32_16x16x32_bf16 v[104:107], v[152:155], v[190:193], v[104:107]
	v_mfma_f32_16x16x32_bf16 v[100:103], v[160:163], v[190:193], v[100:103]
	v_mfma_f32_16x16x32_bf16 v[88:91], v[152:155], v[202:205], v[88:91]
	v_mfma_f32_16x16x32_bf16 v[84:87], v[160:163], v[202:205], v[84:87]
	v_mfma_f32_16x16x32_bf16 v[72:75], v[152:155], v[210:213], v[72:75]
	v_mfma_f32_16x16x32_bf16 v[68:71], v[160:163], v[210:213], v[68:71]
	s_setprio 0
	s_barrier
	s_add_u32 vcc_lo, vcc_lo, s10
	s_addc_u32 vcc_hi, vcc_hi, s11
	s_add_u32 s98, s98, s10
	s_addc_u32 s99, s99, s11
	s_sub_u32 s4, s4, s18
	s_subb_u32 s5, s5, s19
	s_add_u32 s4, s4, s10
	s_addc_u32 s5, s5, s11
	s_add_i32 m0, s9, s26
	ds_read_b128 v[178:181], v223 offset:49152
	ds_read_b128 v[182:185], v223 offset:50176
	ds_read_b128 v[186:189], v223 offset:51200
	ds_read_b128 v[190:193], v223 offset:52224
	ds_read_b128 v[198:201], v223 offset:53248
	ds_read_b128 v[202:205], v223 offset:54272
	ds_read_b128 v[206:209], v223 offset:55296
	ds_read_b128 v[210:213], v223 offset:56320
	global_load_lds_dwordx4 v2, s[98:99]
	s_add_i32 m0, m0, 0x2000
	s_nop 0
	global_load_lds_dwordx4 v168, s[98:99]
	s_add_i32 m0, s15, s26
	s_nop 0
	global_load_lds_dwordx4 v2, vcc
	s_add_i32 m0, m0, 0x2000
	s_nop 0
	global_load_lds_dwordx4 v168, vcc
	s_mov_b32 m0, s77
	s_nop 0
	global_load_lds_dwordx4 v164, s[4:5]
	s_mov_b32 m0, s78
	s_nop 0
	global_load_lds_dwordx4 v166, s[4:5]
	s_waitcnt vmcnt(8)
	s_waitcnt lgkmcnt(0)
	s_barrier
	s_setprio 1
	v_mfma_f32_16x16x32_bf16 v[64:67], v[132:135], v[178:181], v[64:67]
	v_mfma_f32_16x16x32_bf16 v[60:63], v[140:143], v[178:181], v[60:63]
	v_mfma_f32_16x16x32_bf16 v[48:51], v[132:135], v[186:189], v[48:51]
	v_mfma_f32_16x16x32_bf16 v[44:47], v[140:143], v[186:189], v[44:47]
	v_mfma_f32_16x16x32_bf16 v[32:35], v[132:135], v[198:201], v[32:35]
	v_mfma_f32_16x16x32_bf16 v[28:31], v[140:143], v[198:201], v[28:31]
	v_mfma_f32_16x16x32_bf16 v[16:19], v[132:135], v[206:209], v[16:19]
	v_mfma_f32_16x16x32_bf16 v[12:15], v[140:143], v[206:209], v[12:15]
	v_mfma_f32_16x16x32_bf16 v[64:67], v[136:139], v[182:185], v[64:67]
	v_mfma_f32_16x16x32_bf16 v[60:63], v[144:147], v[182:185], v[60:63]
	v_mfma_f32_16x16x32_bf16 v[48:51], v[136:139], v[190:193], v[48:51]
	v_mfma_f32_16x16x32_bf16 v[44:47], v[144:147], v[190:193], v[44:47]
	v_mfma_f32_16x16x32_bf16 v[32:35], v[136:139], v[202:205], v[32:35]
	v_mfma_f32_16x16x32_bf16 v[28:31], v[144:147], v[202:205], v[28:31]
	v_mfma_f32_16x16x32_bf16 v[16:19], v[136:139], v[210:213], v[16:19]
	v_mfma_f32_16x16x32_bf16 v[12:15], v[144:147], v[210:213], v[12:15]
	s_setprio 0
	s_setprio 1
	v_mfma_f32_16x16x32_bf16 v[56:59], v[148:151], v[178:181], v[56:59]
	v_mfma_f32_16x16x32_bf16 v[52:55], v[156:159], v[178:181], v[52:55]
	v_mfma_f32_16x16x32_bf16 v[40:43], v[148:151], v[186:189], v[40:43]
	v_mfma_f32_16x16x32_bf16 v[36:39], v[156:159], v[186:189], v[36:39]
	v_mfma_f32_16x16x32_bf16 v[24:27], v[148:151], v[198:201], v[24:27]
	v_mfma_f32_16x16x32_bf16 v[20:23], v[156:159], v[198:201], v[20:23]
	v_mfma_f32_16x16x32_bf16 v[8:11], v[148:151], v[206:209], v[8:11]
	v_mfma_f32_16x16x32_bf16 v[4:7], v[156:159], v[206:209], v[4:7]
	v_mfma_f32_16x16x32_bf16 v[56:59], v[152:155], v[182:185], v[56:59]
	v_mfma_f32_16x16x32_bf16 v[52:55], v[160:163], v[182:185], v[52:55]
	v_mfma_f32_16x16x32_bf16 v[40:43], v[152:155], v[190:193], v[40:43]
	v_mfma_f32_16x16x32_bf16 v[36:39], v[160:163], v[190:193], v[36:39]
	v_mfma_f32_16x16x32_bf16 v[24:27], v[152:155], v[202:205], v[24:27]
	v_mfma_f32_16x16x32_bf16 v[20:23], v[160:163], v[202:205], v[20:23]
	v_mfma_f32_16x16x32_bf16 v[8:11], v[152:155], v[210:213], v[8:11]
	v_mfma_f32_16x16x32_bf16 v[4:7], v[160:163], v[210:213], v[4:7]
	s_setprio 0
	s_barrier
	s_add_u32 s0, s0, 0x100
	s_addc_u32 s1, s1, 0
	s_add_u32 s6, s6, 0x100
	s_addc_u32 s7, s7, 0
	s_cmp_ge_i32 s8, s80
	s_mov_b32 s4, s8
	s_cbranch_scc0 .LBB0_431
